# K-loop: s_setprio 1 moved before the pre-MMA barrier, repeated lgkmcnt(0) after it dropped, s_setprio 0 moved after the post-MMA barrier
# speedup vs baseline: 1.0331x; 1.0065x over previous
.LBB0_262:
	s_add_i32 vcc_lo, s38, 2
	s_add_u32 s39, s10, 0xfff00080
	s_addc_u32 s66, s11, -1
	s_add_i32 s67, 0, 0x10000
	s_cmp_eq_u32 s35, s38
	s_cselect_b32 s87, s53, s66
	s_cselect_b32 s86, s52, s39
	s_cselect_b32 s39, s13, s49
	s_cselect_b32 s38, s15, s40
	s_add_i32 vcc_hi, 0, 0x14000
	v_add_u32_e32 v142, s67, v1
	v_add_u32_e32 v180, vcc_hi, v1
	ds_read_b128 v[130:133], v142
	ds_read_b128 v[134:137], v142 offset:1024
	ds_read_b128 v[138:141], v142 offset:2048
	ds_read_b128 v[142:145], v142 offset:3072
	ds_read_b128 v[168:171], v180
	ds_read_b128 v[172:175], v180 offset:1024
	ds_read_b128 v[176:179], v180 offset:2048
	ds_read_b128 v[180:183], v180 offset:3072
	v_lshl_add_u64 v[184:185], s[10:11], 0, v[164:165]
	s_add_i32 m0, s85, 0xc000
	ds_read_b128 v[198:201], v197
	ds_read_b128 v[202:205], v197 offset:1024
	ds_read_b128 v[206:209], v197 offset:2048
	ds_read_b128 v[210:213], v197 offset:3072
	ds_read_b128 v[214:217], v197 offset:4096
	ds_read_b128 v[218:221], v197 offset:5120
	ds_read_b128 v[222:225], v197 offset:6144
	ds_read_b128 v[226:229], v197 offset:7168
	global_load_lds_dwordx4 v[184:185], off
	v_lshl_add_u64 v[184:185], s[10:11], 0, v[166:167]
	s_add_i32 m0, s85, 0xe000
	s_nop 0
	global_load_lds_dwordx4 v[184:185], off
	s_waitcnt vmcnt(8)
	s_waitcnt lgkmcnt(0)
	s_setprio 1
	s_barrier
	v_mfma_f32_16x16x32_bf16 v[114:117], v[130:133], v[198:201], v[114:117]
	v_mfma_f32_16x16x32_bf16 v[118:121], v[138:141], v[198:201], v[118:121]
	v_mfma_f32_16x16x32_bf16 v[102:105], v[130:133], v[206:209], v[102:105]
	v_mfma_f32_16x16x32_bf16 v[98:101], v[138:141], v[206:209], v[98:101]
	v_mfma_f32_16x16x32_bf16 v[86:89], v[130:133], v[214:217], v[86:89]
	v_mfma_f32_16x16x32_bf16 v[82:85], v[138:141], v[214:217], v[82:85]
	v_mfma_f32_16x16x32_bf16 v[54:57], v[130:133], v[222:225], v[54:57]
	v_mfma_f32_16x16x32_bf16 v[50:53], v[138:141], v[222:225], v[50:53]
	v_mfma_f32_16x16x32_bf16 v[114:117], v[134:137], v[202:205], v[114:117]
	v_mfma_f32_16x16x32_bf16 v[118:121], v[142:145], v[202:205], v[118:121]
	v_mfma_f32_16x16x32_bf16 v[102:105], v[134:137], v[210:213], v[102:105]
	v_mfma_f32_16x16x32_bf16 v[98:101], v[142:145], v[210:213], v[98:101]
	v_mfma_f32_16x16x32_bf16 v[86:89], v[134:137], v[218:221], v[86:89]
	v_mfma_f32_16x16x32_bf16 v[82:85], v[142:145], v[218:221], v[82:85]
	v_mfma_f32_16x16x32_bf16 v[54:57], v[134:137], v[226:229], v[54:57]
	v_mfma_f32_16x16x32_bf16 v[50:53], v[142:145], v[226:229], v[50:53]
	s_setprio 0
	s_setprio 1
	v_mfma_f32_16x16x32_bf16 v[126:129], v[168:171], v[198:201], v[126:129]
	v_mfma_f32_16x16x32_bf16 v[122:125], v[176:179], v[198:201], v[122:125]
	v_mfma_f32_16x16x32_bf16 v[110:113], v[168:171], v[206:209], v[110:113]
	v_mfma_f32_16x16x32_bf16 v[106:109], v[176:179], v[206:209], v[106:109]
	v_mfma_f32_16x16x32_bf16 v[94:97], v[168:171], v[214:217], v[94:97]
	v_mfma_f32_16x16x32_bf16 v[90:93], v[176:179], v[214:217], v[90:93]
	v_mfma_f32_16x16x32_bf16 v[70:73], v[168:171], v[222:225], v[70:73]
	v_mfma_f32_16x16x32_bf16 v[66:69], v[176:179], v[222:225], v[66:69]
	v_mfma_f32_16x16x32_bf16 v[126:129], v[172:175], v[202:205], v[126:129]
	v_mfma_f32_16x16x32_bf16 v[122:125], v[180:183], v[202:205], v[122:125]
	v_mfma_f32_16x16x32_bf16 v[110:113], v[172:175], v[210:213], v[110:113]
	v_mfma_f32_16x16x32_bf16 v[106:109], v[180:183], v[210:213], v[106:109]
	v_mfma_f32_16x16x32_bf16 v[94:97], v[172:175], v[218:221], v[94:97]
	v_mfma_f32_16x16x32_bf16 v[90:93], v[180:183], v[218:221], v[90:93]
	v_mfma_f32_16x16x32_bf16 v[70:73], v[172:175], v[226:229], v[70:73]
	v_mfma_f32_16x16x32_bf16 v[66:69], v[180:183], v[226:229], v[66:69]
	s_barrier
	s_setprio 0
	s_add_i32 s66, s67, s97
	v_lshl_add_u64 v[184:185], s[38:39], 0, v[156:157]
	s_mov_b32 m0, s66
	ds_read_b128 v[198:201], v197 offset:16384
	ds_read_b128 v[202:205], v197 offset:17408
	ds_read_b128 v[206:209], v197 offset:18432
	ds_read_b128 v[210:213], v197 offset:19456
	ds_read_b128 v[214:217], v197 offset:20480
	ds_read_b128 v[218:221], v197 offset:21504
	ds_read_b128 v[222:225], v197 offset:22528
	ds_read_b128 v[226:229], v197 offset:23552
	global_load_lds_dwordx4 v[184:185], off
	s_add_i32 m0, s66, 0x2000
	s_add_u32 s66, s38, 0x100000
	v_lshl_add_u64 v[230:231], s[38:39], 0, v[160:161]
	s_addc_u32 s67, s39, 0
	s_add_i32 vcc_hi, vcc_hi, s97
	global_load_lds_dwordx4 v[230:231], off
	v_lshl_add_u64 v[232:233], s[66:67], 0, v[156:157]
	s_mov_b32 m0, vcc_hi
	v_lshl_add_u64 v[234:235], s[86:87], 0, v[158:159]
	global_load_lds_dwordx4 v[232:233], off
	v_lshl_add_u64 v[232:233], s[66:67], 0, v[160:161]
	s_add_i32 m0, vcc_hi, 0x2000
	s_nop 0
	global_load_lds_dwordx4 v[232:233], off
	v_lshl_add_u64 v[232:233], s[86:87], 0, v[154:155]
	s_mov_b32 m0, s85
	s_nop 0
	global_load_lds_dwordx4 v[232:233], off
	s_mov_b32 m0, s92
	s_nop 0
	global_load_lds_dwordx4 v[234:235], off
	s_waitcnt vmcnt(8)
	s_waitcnt lgkmcnt(0)
	s_setprio 1
	s_barrier
	v_mfma_f32_16x16x32_bf16 v[62:65], v[130:133], v[198:201], v[62:65]
	v_mfma_f32_16x16x32_bf16 v[58:61], v[138:141], v[198:201], v[58:61]
	v_mfma_f32_16x16x32_bf16 v[38:41], v[130:133], v[206:209], v[38:41]
	v_mfma_f32_16x16x32_bf16 v[34:37], v[138:141], v[206:209], v[34:37]
	v_mfma_f32_16x16x32_bf16 v[22:25], v[130:133], v[214:217], v[22:25]
	v_mfma_f32_16x16x32_bf16 v[18:21], v[138:141], v[214:217], v[18:21]
	v_mfma_f32_16x16x32_bf16 v[6:9], v[130:133], v[222:225], v[6:9]
	v_mfma_f32_16x16x32_bf16 v[2:5], v[138:141], v[222:225], v[2:5]
	v_mfma_f32_16x16x32_bf16 v[62:65], v[134:137], v[202:205], v[62:65]
	v_mfma_f32_16x16x32_bf16 v[58:61], v[142:145], v[202:205], v[58:61]
	v_mfma_f32_16x16x32_bf16 v[38:41], v[134:137], v[210:213], v[38:41]
	v_mfma_f32_16x16x32_bf16 v[34:37], v[142:145], v[210:213], v[34:37]
	v_mfma_f32_16x16x32_bf16 v[22:25], v[134:137], v[218:221], v[22:25]
	v_mfma_f32_16x16x32_bf16 v[18:21], v[142:145], v[218:221], v[18:21]
	v_mfma_f32_16x16x32_bf16 v[6:9], v[134:137], v[226:229], v[6:9]
	v_mfma_f32_16x16x32_bf16 v[2:5], v[142:145], v[226:229], v[2:5]
	s_setprio 0
	s_setprio 1
	v_mfma_f32_16x16x32_bf16 v[78:81], v[168:171], v[198:201], v[78:81]
	v_mfma_f32_16x16x32_bf16 v[74:77], v[176:179], v[198:201], v[74:77]
	v_mfma_f32_16x16x32_bf16 v[46:49], v[168:171], v[206:209], v[46:49]
	v_mfma_f32_16x16x32_bf16 v[42:45], v[176:179], v[206:209], v[42:45]
	v_mfma_f32_16x16x32_bf16 v[30:33], v[168:171], v[214:217], v[30:33]
	v_mfma_f32_16x16x32_bf16 v[26:29], v[176:179], v[214:217], v[26:29]
	v_mfma_f32_16x16x32_bf16 v[14:17], v[168:171], v[222:225], v[14:17]
	v_mfma_f32_16x16x32_bf16 v[10:13], v[176:179], v[222:225], v[10:13]
	v_mfma_f32_16x16x32_bf16 v[78:81], v[172:175], v[202:205], v[78:81]
	v_mfma_f32_16x16x32_bf16 v[74:77], v[180:183], v[202:205], v[74:77]
	v_mfma_f32_16x16x32_bf16 v[46:49], v[172:175], v[210:213], v[46:49]
	v_mfma_f32_16x16x32_bf16 v[42:45], v[180:183], v[210:213], v[42:45]
	v_mfma_f32_16x16x32_bf16 v[30:33], v[172:175], v[218:221], v[30:33]
	v_mfma_f32_16x16x32_bf16 v[26:29], v[180:183], v[218:221], v[26:29]
	v_mfma_f32_16x16x32_bf16 v[14:17], v[172:175], v[226:229], v[14:17]
	v_mfma_f32_16x16x32_bf16 v[10:13], v[180:183], v[226:229], v[10:13]
	s_barrier
	s_setprio 0
	s_add_i32 vcc_hi, 0, 0x18000
	s_add_i32 s56, 0, 0x1c000
	v_add_u32_e32 v142, vcc_hi, v1
	v_add_u32_e32 v180, s56, v1
	ds_read_b128 v[130:133], v142
	ds_read_b128 v[134:137], v142 offset:1024
	ds_read_b128 v[138:141], v142 offset:2048
	ds_read_b128 v[142:145], v142 offset:3072
	ds_read_b128 v[168:171], v180
	ds_read_b128 v[172:175], v180 offset:1024
	ds_read_b128 v[176:179], v180 offset:2048
	ds_read_b128 v[180:183], v180 offset:3072
	s_add_u32 s66, s86, 0x100000
	s_addc_u32 s67, s87, 0
	s_mov_b32 m0, s93
	v_lshl_add_u64 v[236:237], s[66:67], 0, v[154:155]
	ds_read_b128 v[198:201], v197 offset:32768
	ds_read_b128 v[202:205], v197 offset:33792
	ds_read_b128 v[206:209], v197 offset:34816
	ds_read_b128 v[210:213], v197 offset:35840
	ds_read_b128 v[214:217], v197 offset:36864
	ds_read_b128 v[218:221], v197 offset:37888
	ds_read_b128 v[222:225], v197 offset:38912
	ds_read_b128 v[226:229], v197 offset:39936
	global_load_lds_dwordx4 v[236:237], off
	v_lshl_add_u64 v[236:237], s[66:67], 0, v[158:159]
	s_mov_b32 m0, s42
	s_nop 0
	global_load_lds_dwordx4 v[236:237], off
	s_waitcnt vmcnt(8)
	s_waitcnt lgkmcnt(0)
	s_setprio 1
	s_barrier
	v_mfma_f32_16x16x32_bf16 v[114:117], v[130:133], v[198:201], v[114:117]
	v_mfma_f32_16x16x32_bf16 v[118:121], v[138:141], v[198:201], v[118:121]
	v_mfma_f32_16x16x32_bf16 v[102:105], v[130:133], v[206:209], v[102:105]
	v_mfma_f32_16x16x32_bf16 v[98:101], v[138:141], v[206:209], v[98:101]
	v_mfma_f32_16x16x32_bf16 v[86:89], v[130:133], v[214:217], v[86:89]
	v_mfma_f32_16x16x32_bf16 v[82:85], v[138:141], v[214:217], v[82:85]
	v_mfma_f32_16x16x32_bf16 v[54:57], v[130:133], v[222:225], v[54:57]
	v_mfma_f32_16x16x32_bf16 v[50:53], v[138:141], v[222:225], v[50:53]
	v_mfma_f32_16x16x32_bf16 v[114:117], v[134:137], v[202:205], v[114:117]
	v_mfma_f32_16x16x32_bf16 v[118:121], v[142:145], v[202:205], v[118:121]
	v_mfma_f32_16x16x32_bf16 v[102:105], v[134:137], v[210:213], v[102:105]
	v_mfma_f32_16x16x32_bf16 v[98:101], v[142:145], v[210:213], v[98:101]
	v_mfma_f32_16x16x32_bf16 v[86:89], v[134:137], v[218:221], v[86:89]
	v_mfma_f32_16x16x32_bf16 v[82:85], v[142:145], v[218:221], v[82:85]
	v_mfma_f32_16x16x32_bf16 v[54:57], v[134:137], v[226:229], v[54:57]
	v_mfma_f32_16x16x32_bf16 v[50:53], v[142:145], v[226:229], v[50:53]
	s_setprio 0
	s_setprio 1
	v_mfma_f32_16x16x32_bf16 v[126:129], v[168:171], v[198:201], v[126:129]
	v_mfma_f32_16x16x32_bf16 v[122:125], v[176:179], v[198:201], v[122:125]
	v_mfma_f32_16x16x32_bf16 v[110:113], v[168:171], v[206:209], v[110:113]
	v_mfma_f32_16x16x32_bf16 v[106:109], v[176:179], v[206:209], v[106:109]
	v_mfma_f32_16x16x32_bf16 v[94:97], v[168:171], v[214:217], v[94:97]
	v_mfma_f32_16x16x32_bf16 v[90:93], v[176:179], v[214:217], v[90:93]
	v_mfma_f32_16x16x32_bf16 v[70:73], v[168:171], v[222:225], v[70:73]
	v_mfma_f32_16x16x32_bf16 v[66:69], v[176:179], v[222:225], v[66:69]
	v_mfma_f32_16x16x32_bf16 v[126:129], v[172:175], v[202:205], v[126:129]
	v_mfma_f32_16x16x32_bf16 v[122:125], v[180:183], v[202:205], v[122:125]
	v_mfma_f32_16x16x32_bf16 v[110:113], v[172:175], v[210:213], v[110:113]
	v_mfma_f32_16x16x32_bf16 v[106:109], v[180:183], v[210:213], v[106:109]
	v_mfma_f32_16x16x32_bf16 v[94:97], v[172:175], v[218:221], v[94:97]
	v_mfma_f32_16x16x32_bf16 v[90:93], v[180:183], v[218:221], v[90:93]
	v_mfma_f32_16x16x32_bf16 v[70:73], v[172:175], v[226:229], v[70:73]
	v_mfma_f32_16x16x32_bf16 v[66:69], v[180:183], v[226:229], v[66:69]
	s_barrier
	s_setprio 0
	s_add_i32 s57, vcc_hi, s97
	v_lshl_add_u64 v[184:185], v[184:185], 0, s[94:95]
	s_mov_b32 m0, s57
	ds_read_b128 v[198:201], v197 offset:49152
	ds_read_b128 v[202:205], v197 offset:50176
	ds_read_b128 v[206:209], v197 offset:51200
	ds_read_b128 v[210:213], v197 offset:52224
	ds_read_b128 v[214:217], v197 offset:53248
	ds_read_b128 v[218:221], v197 offset:54272
	ds_read_b128 v[222:225], v197 offset:55296
	ds_read_b128 v[226:229], v197 offset:56320
	global_load_lds_dwordx4 v[184:185], off
	s_add_i32 m0, s57, 0x2000
	s_add_u32 s38, s38, 0x100080
	v_lshl_add_u64 v[184:185], v[230:231], 0, s[94:95]
	s_addc_u32 s39, s39, 0
	s_add_i32 s56, s56, s97
	global_load_lds_dwordx4 v[184:185], off
	v_lshl_add_u64 v[184:185], s[38:39], 0, v[156:157]
	s_mov_b32 m0, s56
	s_nop 0
	global_load_lds_dwordx4 v[184:185], off
	v_lshl_add_u64 v[184:185], s[38:39], 0, v[160:161]
	s_add_i32 m0, s56, 0x2000
	s_nop 0
	global_load_lds_dwordx4 v[184:185], off
	v_lshl_add_u64 v[184:185], v[232:233], 0, s[94:95]
	s_mov_b32 m0, s43
	s_nop 0
	global_load_lds_dwordx4 v[184:185], off
	v_lshl_add_u64 v[184:185], v[234:235], 0, s[94:95]
	s_mov_b32 m0, s90
	s_nop 0
	global_load_lds_dwordx4 v[184:185], off
	s_waitcnt vmcnt(8)
	s_waitcnt lgkmcnt(0)
	s_setprio 1
	s_barrier
	v_mfma_f32_16x16x32_bf16 v[62:65], v[130:133], v[198:201], v[62:65]
	v_mfma_f32_16x16x32_bf16 v[58:61], v[138:141], v[198:201], v[58:61]
	v_mfma_f32_16x16x32_bf16 v[38:41], v[130:133], v[206:209], v[38:41]
	v_mfma_f32_16x16x32_bf16 v[34:37], v[138:141], v[206:209], v[34:37]
	v_mfma_f32_16x16x32_bf16 v[22:25], v[130:133], v[214:217], v[22:25]
	v_mfma_f32_16x16x32_bf16 v[18:21], v[138:141], v[214:217], v[18:21]
	v_mfma_f32_16x16x32_bf16 v[6:9], v[130:133], v[222:225], v[6:9]
	v_mfma_f32_16x16x32_bf16 v[2:5], v[138:141], v[222:225], v[2:5]
	v_mfma_f32_16x16x32_bf16 v[62:65], v[134:137], v[202:205], v[62:65]
	v_mfma_f32_16x16x32_bf16 v[58:61], v[142:145], v[202:205], v[58:61]
	v_mfma_f32_16x16x32_bf16 v[38:41], v[134:137], v[210:213], v[38:41]
	v_mfma_f32_16x16x32_bf16 v[34:37], v[142:145], v[210:213], v[34:37]
	v_mfma_f32_16x16x32_bf16 v[22:25], v[134:137], v[218:221], v[22:25]
	v_mfma_f32_16x16x32_bf16 v[18:21], v[142:145], v[218:221], v[18:21]
	v_mfma_f32_16x16x32_bf16 v[6:9], v[134:137], v[226:229], v[6:9]
	v_mfma_f32_16x16x32_bf16 v[2:5], v[142:145], v[226:229], v[2:5]
	s_setprio 0
	s_setprio 1
	v_mfma_f32_16x16x32_bf16 v[78:81], v[168:171], v[198:201], v[78:81]
	v_mfma_f32_16x16x32_bf16 v[74:77], v[176:179], v[198:201], v[74:77]
	v_mfma_f32_16x16x32_bf16 v[46:49], v[168:171], v[206:209], v[46:49]
	v_mfma_f32_16x16x32_bf16 v[42:45], v[176:179], v[206:209], v[42:45]
	v_mfma_f32_16x16x32_bf16 v[30:33], v[168:171], v[214:217], v[30:33]
	v_mfma_f32_16x16x32_bf16 v[26:29], v[176:179], v[214:217], v[26:29]
	v_mfma_f32_16x16x32_bf16 v[14:17], v[168:171], v[222:225], v[14:17]
	v_mfma_f32_16x16x32_bf16 v[10:13], v[176:179], v[222:225], v[10:13]
	v_mfma_f32_16x16x32_bf16 v[78:81], v[172:175], v[202:205], v[78:81]
	v_mfma_f32_16x16x32_bf16 v[74:77], v[180:183], v[202:205], v[74:77]
	v_mfma_f32_16x16x32_bf16 v[46:49], v[172:175], v[210:213], v[46:49]
	v_mfma_f32_16x16x32_bf16 v[42:45], v[180:183], v[210:213], v[42:45]
	v_mfma_f32_16x16x32_bf16 v[30:33], v[172:175], v[218:221], v[30:33]
	v_mfma_f32_16x16x32_bf16 v[26:29], v[180:183], v[218:221], v[26:29]
	v_mfma_f32_16x16x32_bf16 v[14:17], v[172:175], v[226:229], v[14:17]
	v_mfma_f32_16x16x32_bf16 v[10:13], v[180:183], v[226:229], v[10:13]
	s_barrier
	s_setprio 0
	s_add_u32 s40, s40, 0x100
	s_addc_u32 s49, s49, 0
	s_add_u32 s10, s10, 0x100
	s_addc_u32 s11, s11, 0
	s_cmp_ge_u32 vcc_lo, s19
	s_mov_b32 s38, vcc_lo
	s_cbranch_scc0 .LBB0_262
	v_readlane_b32 s10, v254, 27
	v_readlane_b32 s11, v254, 28
	s_and_b64 vcc, exec, s[10:11]
	s_cbranch_vccz .LBB0_270
	s_barrier
	s_cmp_lt_i32 s18, 0
	s_mov_b64 s[10:11], -1
	s_cbranch_scc1 .LBB0_271

.LBB0_1693:
	ds_read_b128 v[128:131], v169
	ds_read_b128 v[132:135], v169 offset:1024
	ds_read_b128 v[136:139], v169 offset:2048
	ds_read_b128 v[140:143], v169 offset:3072
	ds_read_b128 v[158:161], v170
	ds_read_b128 v[162:165], v170 offset:1024
	ds_read_b128 v[172:175], v170 offset:2048
	ds_read_b128 v[176:179], v170 offset:3072
	s_add_u32 s24, s22, 0xfff80080
	s_addc_u32 s25, s23, -1
	s_cmp_eq_u32 s36, 4
	s_cselect_b32 s27, s5, s25
	s_cselect_b32 s26, s4, s24
	s_cselect_b32 s25, s13, s35
	s_cselect_b32 s24, s15, s34
	v_lshl_add_u64 v[212:213], s[22:23], 0, v[152:153]
	s_add_i32 m0, s94, 0xc000
	ds_read_b128 v[180:183], v171
	ds_read_b128 v[184:187], v171 offset:1024
	ds_read_b128 v[188:191], v171 offset:2048
	ds_read_b128 v[192:195], v171 offset:3072
	ds_read_b128 v[196:199], v171 offset:4096
	ds_read_b128 v[200:203], v171 offset:5120
	ds_read_b128 v[204:207], v171 offset:6144
	ds_read_b128 v[208:211], v171 offset:7168
	global_load_lds_dwordx4 v[212:213], off
	v_lshl_add_u64 v[212:213], s[22:23], 0, v[154:155]
	s_add_i32 m0, s94, 0xe000
	s_nop 0
	global_load_lds_dwordx4 v[212:213], off
	s_waitcnt vmcnt(8)
	s_waitcnt lgkmcnt(0)
	s_setprio 1
	s_barrier
	v_mfma_f32_16x16x32_bf16 v[80:83], v[128:131], v[180:183], v[80:83]
	v_mfma_f32_16x16x32_bf16 v[92:95], v[136:139], v[180:183], v[92:95]
	v_mfma_f32_16x16x32_bf16 v[84:87], v[128:131], v[188:191], v[84:87]
	v_mfma_f32_16x16x32_bf16 v[96:99], v[136:139], v[188:191], v[96:99]
	v_mfma_f32_16x16x32_bf16 v[88:91], v[128:131], v[196:199], v[88:91]
	v_mfma_f32_16x16x32_bf16 v[100:103], v[136:139], v[196:199], v[100:103]
	v_mfma_f32_16x16x32_bf16 v[72:75], v[128:131], v[204:207], v[72:75]
	v_mfma_f32_16x16x32_bf16 v[76:79], v[136:139], v[204:207], v[76:79]
	v_mfma_f32_16x16x32_bf16 v[80:83], v[132:135], v[184:187], v[80:83]
	v_mfma_f32_16x16x32_bf16 v[92:95], v[140:143], v[184:187], v[92:95]
	v_mfma_f32_16x16x32_bf16 v[84:87], v[132:135], v[192:195], v[84:87]
	v_mfma_f32_16x16x32_bf16 v[96:99], v[140:143], v[192:195], v[96:99]
	v_mfma_f32_16x16x32_bf16 v[88:91], v[132:135], v[200:203], v[88:91]
	v_mfma_f32_16x16x32_bf16 v[100:103], v[140:143], v[200:203], v[100:103]
	v_mfma_f32_16x16x32_bf16 v[72:75], v[132:135], v[208:211], v[72:75]
	v_mfma_f32_16x16x32_bf16 v[76:79], v[140:143], v[208:211], v[76:79]
	s_setprio 0
	s_setprio 1
	v_mfma_f32_16x16x32_bf16 v[104:107], v[158:161], v[180:183], v[104:107]
	v_mfma_f32_16x16x32_bf16 v[116:119], v[172:175], v[180:183], v[116:119]
	v_mfma_f32_16x16x32_bf16 v[108:111], v[158:161], v[188:191], v[108:111]
	v_mfma_f32_16x16x32_bf16 v[120:123], v[172:175], v[188:191], v[120:123]
	v_mfma_f32_16x16x32_bf16 v[112:115], v[158:161], v[196:199], v[112:115]
	v_mfma_f32_16x16x32_bf16 v[124:127], v[172:175], v[196:199], v[124:127]
	v_mfma_f32_16x16x32_bf16 v[68:71], v[158:161], v[204:207], v[68:71]
	v_mfma_f32_16x16x32_bf16 v[64:67], v[172:175], v[204:207], v[64:67]
	v_mfma_f32_16x16x32_bf16 v[104:107], v[162:165], v[184:187], v[104:107]
	v_mfma_f32_16x16x32_bf16 v[116:119], v[176:179], v[184:187], v[116:119]
	v_mfma_f32_16x16x32_bf16 v[108:111], v[162:165], v[192:195], v[108:111]
	v_mfma_f32_16x16x32_bf16 v[120:123], v[176:179], v[192:195], v[120:123]
	v_mfma_f32_16x16x32_bf16 v[112:115], v[162:165], v[200:203], v[112:115]
	v_mfma_f32_16x16x32_bf16 v[124:127], v[176:179], v[200:203], v[124:127]
	v_mfma_f32_16x16x32_bf16 v[68:71], v[162:165], v[208:211], v[68:71]
	v_mfma_f32_16x16x32_bf16 v[64:67], v[176:179], v[208:211], v[64:67]
	s_barrier
	s_setprio 0
	s_add_i32 s37, s31, s97
	v_lshl_add_u64 v[212:213], s[24:25], 0, v[148:149]
	s_mov_b32 m0, s37
	ds_read_b128 v[180:183], v171 offset:16384
	ds_read_b128 v[184:187], v171 offset:17408
	ds_read_b128 v[188:191], v171 offset:18432
	ds_read_b128 v[192:195], v171 offset:19456
	ds_read_b128 v[196:199], v171 offset:20480
	ds_read_b128 v[200:203], v171 offset:21504
	ds_read_b128 v[204:207], v171 offset:22528
	ds_read_b128 v[208:211], v171 offset:23552
	global_load_lds_dwordx4 v[212:213], off
	s_add_i32 m0, s37, 0x2000
	s_add_u32 s38, s24, 0x20000
	v_lshl_add_u64 v[214:215], s[24:25], 0, v[144:145]
	s_addc_u32 s39, s25, 0
	s_add_i32 s37, s33, s97
	global_load_lds_dwordx4 v[214:215], off
	v_lshl_add_u64 v[216:217], s[38:39], 0, v[148:149]
	s_mov_b32 m0, s37
	v_lshl_add_u64 v[218:219], s[26:27], 0, v[146:147]
	global_load_lds_dwordx4 v[216:217], off
	v_lshl_add_u64 v[216:217], s[38:39], 0, v[144:145]
	s_add_i32 m0, s37, 0x2000
	s_nop 0
	global_load_lds_dwordx4 v[216:217], off
	v_lshl_add_u64 v[216:217], s[26:27], 0, v[150:151]
	s_mov_b32 m0, s94
	s_nop 0
	global_load_lds_dwordx4 v[216:217], off
	s_mov_b32 m0, s3
	s_nop 0
	global_load_lds_dwordx4 v[218:219], off
	s_waitcnt vmcnt(8)
	s_waitcnt lgkmcnt(0)
	s_setprio 1
	s_barrier
	v_mfma_f32_16x16x32_bf16 v[48:51], v[128:131], v[180:183], v[48:51]
	v_mfma_f32_16x16x32_bf16 v[52:55], v[136:139], v[180:183], v[52:55]
	v_mfma_f32_16x16x32_bf16 v[32:35], v[128:131], v[188:191], v[32:35]
	v_mfma_f32_16x16x32_bf16 v[36:39], v[136:139], v[188:191], v[36:39]
	v_mfma_f32_16x16x32_bf16 v[16:19], v[128:131], v[196:199], v[16:19]
	v_mfma_f32_16x16x32_bf16 v[20:23], v[136:139], v[196:199], v[20:23]
	v_mfma_f32_16x16x32_bf16 v[0:3], v[128:131], v[204:207], v[0:3]
	v_mfma_f32_16x16x32_bf16 v[4:7], v[136:139], v[204:207], v[4:7]
	v_mfma_f32_16x16x32_bf16 v[48:51], v[132:135], v[184:187], v[48:51]
	v_mfma_f32_16x16x32_bf16 v[52:55], v[140:143], v[184:187], v[52:55]
	v_mfma_f32_16x16x32_bf16 v[32:35], v[132:135], v[192:195], v[32:35]
	v_mfma_f32_16x16x32_bf16 v[36:39], v[140:143], v[192:195], v[36:39]
	v_mfma_f32_16x16x32_bf16 v[16:19], v[132:135], v[200:203], v[16:19]
	v_mfma_f32_16x16x32_bf16 v[20:23], v[140:143], v[200:203], v[20:23]
	v_mfma_f32_16x16x32_bf16 v[0:3], v[132:135], v[208:211], v[0:3]
	v_mfma_f32_16x16x32_bf16 v[4:7], v[140:143], v[208:211], v[4:7]
	s_setprio 0
	s_setprio 1
	v_mfma_f32_16x16x32_bf16 v[56:59], v[158:161], v[180:183], v[56:59]
	v_mfma_f32_16x16x32_bf16 v[60:63], v[172:175], v[180:183], v[60:63]
	v_mfma_f32_16x16x32_bf16 v[40:43], v[158:161], v[188:191], v[40:43]
	v_mfma_f32_16x16x32_bf16 v[44:47], v[172:175], v[188:191], v[44:47]
	v_mfma_f32_16x16x32_bf16 v[24:27], v[158:161], v[196:199], v[24:27]
	v_mfma_f32_16x16x32_bf16 v[28:31], v[172:175], v[196:199], v[28:31]
	v_mfma_f32_16x16x32_bf16 v[8:11], v[158:161], v[204:207], v[8:11]
	v_mfma_f32_16x16x32_bf16 v[12:15], v[172:175], v[204:207], v[12:15]
	v_mfma_f32_16x16x32_bf16 v[56:59], v[162:165], v[184:187], v[56:59]
	v_mfma_f32_16x16x32_bf16 v[60:63], v[176:179], v[184:187], v[60:63]
	v_mfma_f32_16x16x32_bf16 v[40:43], v[162:165], v[192:195], v[40:43]
	v_mfma_f32_16x16x32_bf16 v[44:47], v[176:179], v[192:195], v[44:47]
	v_mfma_f32_16x16x32_bf16 v[24:27], v[162:165], v[200:203], v[24:27]
	v_mfma_f32_16x16x32_bf16 v[28:31], v[176:179], v[200:203], v[28:31]
	v_mfma_f32_16x16x32_bf16 v[8:11], v[162:165], v[208:211], v[8:11]
	v_mfma_f32_16x16x32_bf16 v[12:15], v[176:179], v[208:211], v[12:15]
	s_barrier
	s_setprio 0
	s_add_i32 s37, 0, 0x18000
	s_add_i32 s38, 0, 0x1c000
	v_add_u32_e32 v140, s37, v167
	v_add_u32_e32 v176, s38, v167
	ds_read_b128 v[128:131], v140
	ds_read_b128 v[132:135], v140 offset:1024
	ds_read_b128 v[136:139], v140 offset:2048
	ds_read_b128 v[140:143], v140 offset:3072
	ds_read_b128 v[158:161], v176
	ds_read_b128 v[162:165], v176 offset:1024
	ds_read_b128 v[172:175], v176 offset:2048
	ds_read_b128 v[176:179], v176 offset:3072
	s_add_u32 s26, s26, 0x80000
	s_addc_u32 s27, s27, 0
	s_mov_b32 m0, s7
	v_lshl_add_u64 v[220:221], s[26:27], 0, v[150:151]
	ds_read_b128 v[180:183], v171 offset:32768
	ds_read_b128 v[184:187], v171 offset:33792
	ds_read_b128 v[188:191], v171 offset:34816
	ds_read_b128 v[192:195], v171 offset:35840
	ds_read_b128 v[196:199], v171 offset:36864
	ds_read_b128 v[200:203], v171 offset:37888
	ds_read_b128 v[204:207], v171 offset:38912
	ds_read_b128 v[208:211], v171 offset:39936
	global_load_lds_dwordx4 v[220:221], off
	v_lshl_add_u64 v[220:221], s[26:27], 0, v[146:147]
	s_mov_b32 m0, s19
	s_nop 0
	global_load_lds_dwordx4 v[220:221], off
	s_waitcnt vmcnt(8)
	s_waitcnt lgkmcnt(0)
	s_setprio 1
	s_barrier
	v_mfma_f32_16x16x32_bf16 v[80:83], v[128:131], v[180:183], v[80:83]
	v_mfma_f32_16x16x32_bf16 v[92:95], v[136:139], v[180:183], v[92:95]
	v_mfma_f32_16x16x32_bf16 v[84:87], v[128:131], v[188:191], v[84:87]
	v_mfma_f32_16x16x32_bf16 v[96:99], v[136:139], v[188:191], v[96:99]
	v_mfma_f32_16x16x32_bf16 v[88:91], v[128:131], v[196:199], v[88:91]
	v_mfma_f32_16x16x32_bf16 v[100:103], v[136:139], v[196:199], v[100:103]
	v_mfma_f32_16x16x32_bf16 v[72:75], v[128:131], v[204:207], v[72:75]
	v_mfma_f32_16x16x32_bf16 v[76:79], v[136:139], v[204:207], v[76:79]
	v_mfma_f32_16x16x32_bf16 v[80:83], v[132:135], v[184:187], v[80:83]
	v_mfma_f32_16x16x32_bf16 v[92:95], v[140:143], v[184:187], v[92:95]
	v_mfma_f32_16x16x32_bf16 v[84:87], v[132:135], v[192:195], v[84:87]
	v_mfma_f32_16x16x32_bf16 v[96:99], v[140:143], v[192:195], v[96:99]
	v_mfma_f32_16x16x32_bf16 v[88:91], v[132:135], v[200:203], v[88:91]
	v_mfma_f32_16x16x32_bf16 v[100:103], v[140:143], v[200:203], v[100:103]
	v_mfma_f32_16x16x32_bf16 v[72:75], v[132:135], v[208:211], v[72:75]
	v_mfma_f32_16x16x32_bf16 v[76:79], v[140:143], v[208:211], v[76:79]
	s_setprio 0
	s_setprio 1
	v_mfma_f32_16x16x32_bf16 v[104:107], v[158:161], v[180:183], v[104:107]
	v_mfma_f32_16x16x32_bf16 v[116:119], v[172:175], v[180:183], v[116:119]
	v_mfma_f32_16x16x32_bf16 v[108:111], v[158:161], v[188:191], v[108:111]
	v_mfma_f32_16x16x32_bf16 v[120:123], v[172:175], v[188:191], v[120:123]
	v_mfma_f32_16x16x32_bf16 v[112:115], v[158:161], v[196:199], v[112:115]
	v_mfma_f32_16x16x32_bf16 v[124:127], v[172:175], v[196:199], v[124:127]
	v_mfma_f32_16x16x32_bf16 v[68:71], v[158:161], v[204:207], v[68:71]
	v_mfma_f32_16x16x32_bf16 v[64:67], v[172:175], v[204:207], v[64:67]
	v_mfma_f32_16x16x32_bf16 v[104:107], v[162:165], v[184:187], v[104:107]
	v_mfma_f32_16x16x32_bf16 v[116:119], v[176:179], v[184:187], v[116:119]
	v_mfma_f32_16x16x32_bf16 v[108:111], v[162:165], v[192:195], v[108:111]
	v_mfma_f32_16x16x32_bf16 v[120:123], v[176:179], v[192:195], v[120:123]
	v_mfma_f32_16x16x32_bf16 v[112:115], v[162:165], v[200:203], v[112:115]
	v_mfma_f32_16x16x32_bf16 v[124:127], v[176:179], v[200:203], v[124:127]
	v_mfma_f32_16x16x32_bf16 v[68:71], v[162:165], v[208:211], v[68:71]
	v_mfma_f32_16x16x32_bf16 v[64:67], v[176:179], v[208:211], v[64:67]
	s_barrier
	s_setprio 0
	s_add_i32 s26, s37, s97
	v_lshl_add_u64 v[212:213], v[212:213], 0, s[0:1]
	s_mov_b32 m0, s26
	ds_read_b128 v[180:183], v171 offset:49152
	ds_read_b128 v[184:187], v171 offset:50176
	ds_read_b128 v[188:191], v171 offset:51200
	ds_read_b128 v[192:195], v171 offset:52224
	ds_read_b128 v[196:199], v171 offset:53248
	ds_read_b128 v[200:203], v171 offset:54272
	ds_read_b128 v[204:207], v171 offset:55296
	ds_read_b128 v[208:211], v171 offset:56320
	global_load_lds_dwordx4 v[212:213], off
	s_add_i32 m0, s26, 0x2000
	s_add_u32 s24, s24, 0x20080
	v_lshl_add_u64 v[212:213], v[214:215], 0, s[0:1]
	s_addc_u32 s25, s25, 0
	s_add_i32 s26, s38, s97
	global_load_lds_dwordx4 v[212:213], off
	v_lshl_add_u64 v[212:213], s[24:25], 0, v[148:149]
	s_mov_b32 m0, s26
	s_nop 0
	global_load_lds_dwordx4 v[212:213], off
	v_lshl_add_u64 v[212:213], s[24:25], 0, v[144:145]
	s_add_i32 m0, s26, 0x2000
	s_nop 0
	global_load_lds_dwordx4 v[212:213], off
	v_lshl_add_u64 v[212:213], v[216:217], 0, s[0:1]
	s_mov_b32 m0, s28
	s_nop 0
	global_load_lds_dwordx4 v[212:213], off
	v_lshl_add_u64 v[212:213], v[218:219], 0, s[0:1]
	s_mov_b32 m0, s29
	s_nop 0
	global_load_lds_dwordx4 v[212:213], off
	s_waitcnt vmcnt(8)
	s_waitcnt lgkmcnt(0)
	s_setprio 1
	s_barrier
	v_mfma_f32_16x16x32_bf16 v[48:51], v[128:131], v[180:183], v[48:51]
	v_mfma_f32_16x16x32_bf16 v[52:55], v[136:139], v[180:183], v[52:55]
	v_mfma_f32_16x16x32_bf16 v[32:35], v[128:131], v[188:191], v[32:35]
	v_mfma_f32_16x16x32_bf16 v[36:39], v[136:139], v[188:191], v[36:39]
	v_mfma_f32_16x16x32_bf16 v[16:19], v[128:131], v[196:199], v[16:19]
	v_mfma_f32_16x16x32_bf16 v[20:23], v[136:139], v[196:199], v[20:23]
	v_mfma_f32_16x16x32_bf16 v[0:3], v[128:131], v[204:207], v[0:3]
	v_mfma_f32_16x16x32_bf16 v[4:7], v[136:139], v[204:207], v[4:7]
	v_mfma_f32_16x16x32_bf16 v[48:51], v[132:135], v[184:187], v[48:51]
	v_mfma_f32_16x16x32_bf16 v[52:55], v[140:143], v[184:187], v[52:55]
	v_mfma_f32_16x16x32_bf16 v[32:35], v[132:135], v[192:195], v[32:35]
	v_mfma_f32_16x16x32_bf16 v[36:39], v[140:143], v[192:195], v[36:39]
	v_mfma_f32_16x16x32_bf16 v[16:19], v[132:135], v[200:203], v[16:19]
	v_mfma_f32_16x16x32_bf16 v[20:23], v[140:143], v[200:203], v[20:23]
	v_mfma_f32_16x16x32_bf16 v[0:3], v[132:135], v[208:211], v[0:3]
	v_mfma_f32_16x16x32_bf16 v[4:7], v[140:143], v[208:211], v[4:7]
	s_setprio 0
	s_setprio 1
	v_mfma_f32_16x16x32_bf16 v[56:59], v[158:161], v[180:183], v[56:59]
	v_mfma_f32_16x16x32_bf16 v[60:63], v[172:175], v[180:183], v[60:63]
	v_mfma_f32_16x16x32_bf16 v[40:43], v[158:161], v[188:191], v[40:43]
	v_mfma_f32_16x16x32_bf16 v[44:47], v[172:175], v[188:191], v[44:47]
	v_mfma_f32_16x16x32_bf16 v[24:27], v[158:161], v[196:199], v[24:27]
	v_mfma_f32_16x16x32_bf16 v[28:31], v[172:175], v[196:199], v[28:31]
	v_mfma_f32_16x16x32_bf16 v[8:11], v[158:161], v[204:207], v[8:11]
	v_mfma_f32_16x16x32_bf16 v[12:15], v[172:175], v[204:207], v[12:15]
	v_mfma_f32_16x16x32_bf16 v[56:59], v[162:165], v[184:187], v[56:59]
	v_mfma_f32_16x16x32_bf16 v[60:63], v[176:179], v[184:187], v[60:63]
	v_mfma_f32_16x16x32_bf16 v[40:43], v[162:165], v[192:195], v[40:43]
	v_mfma_f32_16x16x32_bf16 v[44:47], v[176:179], v[192:195], v[44:47]
	v_mfma_f32_16x16x32_bf16 v[24:27], v[162:165], v[200:203], v[24:27]
	v_mfma_f32_16x16x32_bf16 v[28:31], v[176:179], v[200:203], v[28:31]
	v_mfma_f32_16x16x32_bf16 v[8:11], v[162:165], v[208:211], v[8:11]
	v_mfma_f32_16x16x32_bf16 v[12:15], v[176:179], v[208:211], v[12:15]
	s_barrier
	s_setprio 0
	s_add_i32 s36, s36, 2
	s_add_u32 s34, s34, 0x100
	s_addc_u32 s35, s35, 0
	s_add_u32 s22, s22, 0x100
	s_addc_u32 s23, s23, 0
	s_cmp_gt_u32 s36, 5
	s_cbranch_scc0 .LBB0_1693
	v_readlane_b32 s22, v254, 27
	v_readlane_b32 s23, v254, 28
	s_and_b64 vcc, exec, s[22:23]
	s_cbranch_vccz .LBB0_1696
	s_barrier

.LBB0_2020:
	ds_read_b128 v[128:131], v244
	ds_read_b128 v[132:135], v244 offset:1024
	ds_read_b128 v[136:139], v244 offset:2048
	ds_read_b128 v[140:143], v244 offset:3072
	ds_read_b128 v[144:147], v245
	ds_read_b128 v[148:151], v245 offset:1024
	ds_read_b128 v[152:155], v245 offset:2048
	ds_read_b128 v[156:159], v245 offset:3072
	s_add_i32 s71, s46, 2
	s_add_u32 s47, s44, 0xfff00080
	s_addc_u32 s48, s45, -1
	s_cmp_eq_u32 s68, s46
	s_cselect_b32 s46, s43, s69
	s_cselect_b32 s49, s5, s48
	s_cselect_b32 s48, s23, s47
	s_cselect_b32 s47, s21, s70
	v_lshl_add_u64 v[192:193], s[44:45], 0, v[218:219]
	s_add_i32 m0, s94, 0xc000
	ds_read_b128 v[160:163], v246
	ds_read_b128 v[164:167], v246 offset:1024
	ds_read_b128 v[168:171], v246 offset:2048
	ds_read_b128 v[172:175], v246 offset:3072
	ds_read_b128 v[176:179], v246 offset:4096
	ds_read_b128 v[180:183], v246 offset:5120
	ds_read_b128 v[184:187], v246 offset:6144
	ds_read_b128 v[188:191], v246 offset:7168
	global_load_lds_dwordx4 v[192:193], off
	v_lshl_add_u64 v[192:193], s[44:45], 0, v[220:221]
	s_add_i32 m0, s94, 0xe000
	s_nop 0
	global_load_lds_dwordx4 v[192:193], off
	s_waitcnt vmcnt(8)
	s_waitcnt lgkmcnt(0)
	s_setprio 1
	s_barrier
	v_mfma_f32_16x16x32_bf16 v[112:115], v[128:131], v[160:163], v[112:115]
	v_mfma_f32_16x16x32_bf16 v[116:119], v[136:139], v[160:163], v[116:119]
	v_mfma_f32_16x16x32_bf16 v[100:103], v[128:131], v[168:171], v[100:103]
	v_mfma_f32_16x16x32_bf16 v[96:99], v[136:139], v[168:171], v[96:99]
	v_mfma_f32_16x16x32_bf16 v[84:87], v[128:131], v[176:179], v[84:87]
	v_mfma_f32_16x16x32_bf16 v[80:83], v[136:139], v[176:179], v[80:83]
	v_mfma_f32_16x16x32_bf16 v[52:55], v[128:131], v[184:187], v[52:55]
	v_mfma_f32_16x16x32_bf16 v[48:51], v[136:139], v[184:187], v[48:51]
	v_mfma_f32_16x16x32_bf16 v[112:115], v[132:135], v[164:167], v[112:115]
	v_mfma_f32_16x16x32_bf16 v[116:119], v[140:143], v[164:167], v[116:119]
	v_mfma_f32_16x16x32_bf16 v[100:103], v[132:135], v[172:175], v[100:103]
	v_mfma_f32_16x16x32_bf16 v[96:99], v[140:143], v[172:175], v[96:99]
	v_mfma_f32_16x16x32_bf16 v[84:87], v[132:135], v[180:183], v[84:87]
	v_mfma_f32_16x16x32_bf16 v[80:83], v[140:143], v[180:183], v[80:83]
	v_mfma_f32_16x16x32_bf16 v[52:55], v[132:135], v[188:191], v[52:55]
	v_mfma_f32_16x16x32_bf16 v[48:51], v[140:143], v[188:191], v[48:51]
	s_setprio 0
	s_setprio 1
	v_mfma_f32_16x16x32_bf16 v[124:127], v[144:147], v[160:163], v[124:127]
	v_mfma_f32_16x16x32_bf16 v[120:123], v[152:155], v[160:163], v[120:123]
	v_mfma_f32_16x16x32_bf16 v[108:111], v[144:147], v[168:171], v[108:111]
	v_mfma_f32_16x16x32_bf16 v[104:107], v[152:155], v[168:171], v[104:107]
	v_mfma_f32_16x16x32_bf16 v[92:95], v[144:147], v[176:179], v[92:95]
	v_mfma_f32_16x16x32_bf16 v[88:91], v[152:155], v[176:179], v[88:91]
	v_mfma_f32_16x16x32_bf16 v[68:71], v[144:147], v[184:187], v[68:71]
	v_mfma_f32_16x16x32_bf16 v[64:67], v[152:155], v[184:187], v[64:67]
	v_mfma_f32_16x16x32_bf16 v[124:127], v[148:151], v[164:167], v[124:127]
	v_mfma_f32_16x16x32_bf16 v[120:123], v[156:159], v[164:167], v[120:123]
	v_mfma_f32_16x16x32_bf16 v[108:111], v[148:151], v[172:175], v[108:111]
	v_mfma_f32_16x16x32_bf16 v[104:107], v[156:159], v[172:175], v[104:107]
	v_mfma_f32_16x16x32_bf16 v[92:95], v[148:151], v[180:183], v[92:95]
	v_mfma_f32_16x16x32_bf16 v[88:91], v[156:159], v[180:183], v[88:91]
	v_mfma_f32_16x16x32_bf16 v[68:71], v[148:151], v[188:191], v[68:71]
	v_mfma_f32_16x16x32_bf16 v[64:67], v[156:159], v[188:191], v[64:67]
	s_barrier
	s_setprio 0
	s_add_i32 s76, s60, s97
	v_lshl_add_u64 v[192:193], s[46:47], 0, v[210:211]
	s_mov_b32 m0, s76
	ds_read_b128 v[160:163], v246 offset:16384
	ds_read_b128 v[164:167], v246 offset:17408
	ds_read_b128 v[168:171], v246 offset:18432
	ds_read_b128 v[172:175], v246 offset:19456
	ds_read_b128 v[176:179], v246 offset:20480
	ds_read_b128 v[180:183], v246 offset:21504
	ds_read_b128 v[184:187], v246 offset:22528
	ds_read_b128 v[188:191], v246 offset:23552
	global_load_lds_dwordx4 v[192:193], off
	s_add_i32 m0, s76, 0x2000
	s_add_u32 s76, s46, 0x100000
	v_lshl_add_u64 v[194:195], s[46:47], 0, v[214:215]
	s_addc_u32 s77, s47, 0
	s_add_i32 s78, s61, s97
	global_load_lds_dwordx4 v[194:195], off
	v_lshl_add_u64 v[196:197], s[76:77], 0, v[210:211]
	s_mov_b32 m0, s78
	v_lshl_add_u64 v[198:199], s[48:49], 0, v[212:213]
	global_load_lds_dwordx4 v[196:197], off
	v_lshl_add_u64 v[196:197], s[76:77], 0, v[214:215]
	s_add_i32 m0, s78, 0x2000
	s_nop 0
	global_load_lds_dwordx4 v[196:197], off
	v_lshl_add_u64 v[196:197], s[48:49], 0, v[208:209]
	s_mov_b32 m0, s94
	s_nop 0
	global_load_lds_dwordx4 v[196:197], off
	s_mov_b32 m0, s2
	s_nop 0
	global_load_lds_dwordx4 v[198:199], off
	s_waitcnt vmcnt(8)
	s_waitcnt lgkmcnt(0)
	s_setprio 1
	s_barrier
	v_mfma_f32_16x16x32_bf16 v[60:63], v[128:131], v[160:163], v[60:63]
	v_mfma_f32_16x16x32_bf16 v[56:59], v[136:139], v[160:163], v[56:59]
	v_mfma_f32_16x16x32_bf16 v[36:39], v[128:131], v[168:171], v[36:39]
	v_mfma_f32_16x16x32_bf16 v[32:35], v[136:139], v[168:171], v[32:35]
	v_mfma_f32_16x16x32_bf16 v[20:23], v[128:131], v[176:179], v[20:23]
	v_mfma_f32_16x16x32_bf16 v[16:19], v[136:139], v[176:179], v[16:19]
	v_mfma_f32_16x16x32_bf16 v[4:7], v[128:131], v[184:187], v[4:7]
	v_mfma_f32_16x16x32_bf16 v[0:3], v[136:139], v[184:187], v[0:3]
	v_mfma_f32_16x16x32_bf16 v[60:63], v[132:135], v[164:167], v[60:63]
	v_mfma_f32_16x16x32_bf16 v[56:59], v[140:143], v[164:167], v[56:59]
	v_mfma_f32_16x16x32_bf16 v[36:39], v[132:135], v[172:175], v[36:39]
	v_mfma_f32_16x16x32_bf16 v[32:35], v[140:143], v[172:175], v[32:35]
	v_mfma_f32_16x16x32_bf16 v[20:23], v[132:135], v[180:183], v[20:23]
	v_mfma_f32_16x16x32_bf16 v[16:19], v[140:143], v[180:183], v[16:19]
	v_mfma_f32_16x16x32_bf16 v[4:7], v[132:135], v[188:191], v[4:7]
	v_mfma_f32_16x16x32_bf16 v[0:3], v[140:143], v[188:191], v[0:3]
	s_setprio 0
	s_setprio 1
	v_mfma_f32_16x16x32_bf16 v[76:79], v[144:147], v[160:163], v[76:79]
	v_mfma_f32_16x16x32_bf16 v[72:75], v[152:155], v[160:163], v[72:75]
	v_mfma_f32_16x16x32_bf16 v[44:47], v[144:147], v[168:171], v[44:47]
	v_mfma_f32_16x16x32_bf16 v[40:43], v[152:155], v[168:171], v[40:43]
	v_mfma_f32_16x16x32_bf16 v[28:31], v[144:147], v[176:179], v[28:31]
	v_mfma_f32_16x16x32_bf16 v[24:27], v[152:155], v[176:179], v[24:27]
	v_mfma_f32_16x16x32_bf16 v[12:15], v[144:147], v[184:187], v[12:15]
	v_mfma_f32_16x16x32_bf16 v[8:11], v[152:155], v[184:187], v[8:11]
	v_mfma_f32_16x16x32_bf16 v[76:79], v[148:151], v[164:167], v[76:79]
	v_mfma_f32_16x16x32_bf16 v[72:75], v[156:159], v[164:167], v[72:75]
	v_mfma_f32_16x16x32_bf16 v[44:47], v[148:151], v[172:175], v[44:47]
	v_mfma_f32_16x16x32_bf16 v[40:43], v[156:159], v[172:175], v[40:43]
	v_mfma_f32_16x16x32_bf16 v[28:31], v[148:151], v[180:183], v[28:31]
	v_mfma_f32_16x16x32_bf16 v[24:27], v[156:159], v[180:183], v[24:27]
	v_mfma_f32_16x16x32_bf16 v[12:15], v[148:151], v[188:191], v[12:15]
	v_mfma_f32_16x16x32_bf16 v[8:11], v[156:159], v[188:191], v[8:11]
	s_barrier
	s_setprio 0
	s_add_i32 s76, 0, 0x18000
	s_add_i32 s77, 0, 0x1c000
	v_add_u32_e32 v140, s76, v243
	v_add_u32_e32 v156, s77, v243
	ds_read_b128 v[128:131], v140
	ds_read_b128 v[132:135], v140 offset:1024
	ds_read_b128 v[136:139], v140 offset:2048
	ds_read_b128 v[140:143], v140 offset:3072
	ds_read_b128 v[144:147], v156
	ds_read_b128 v[148:151], v156 offset:1024
	ds_read_b128 v[152:155], v156 offset:2048
	ds_read_b128 v[156:159], v156 offset:3072
	s_add_u32 s48, s48, 0x100000
	s_addc_u32 s49, s49, 0
	s_mov_b32 m0, s3
	v_lshl_add_u64 v[200:201], s[48:49], 0, v[208:209]
	ds_read_b128 v[160:163], v246 offset:32768
	ds_read_b128 v[164:167], v246 offset:33792
	ds_read_b128 v[168:171], v246 offset:34816
	ds_read_b128 v[172:175], v246 offset:35840
	ds_read_b128 v[176:179], v246 offset:36864
	ds_read_b128 v[180:183], v246 offset:37888
	ds_read_b128 v[184:187], v246 offset:38912
	ds_read_b128 v[188:191], v246 offset:39936
	global_load_lds_dwordx4 v[200:201], off
	v_lshl_add_u64 v[200:201], s[48:49], 0, v[212:213]
	s_mov_b32 m0, s33
	s_nop 0
	global_load_lds_dwordx4 v[200:201], off
	s_waitcnt vmcnt(8)
	s_waitcnt lgkmcnt(0)
	s_setprio 1
	s_barrier
	v_mfma_f32_16x16x32_bf16 v[112:115], v[128:131], v[160:163], v[112:115]
	v_mfma_f32_16x16x32_bf16 v[116:119], v[136:139], v[160:163], v[116:119]
	v_mfma_f32_16x16x32_bf16 v[100:103], v[128:131], v[168:171], v[100:103]
	v_mfma_f32_16x16x32_bf16 v[96:99], v[136:139], v[168:171], v[96:99]
	v_mfma_f32_16x16x32_bf16 v[84:87], v[128:131], v[176:179], v[84:87]
	v_mfma_f32_16x16x32_bf16 v[80:83], v[136:139], v[176:179], v[80:83]
	v_mfma_f32_16x16x32_bf16 v[52:55], v[128:131], v[184:187], v[52:55]
	v_mfma_f32_16x16x32_bf16 v[48:51], v[136:139], v[184:187], v[48:51]
	v_mfma_f32_16x16x32_bf16 v[112:115], v[132:135], v[164:167], v[112:115]
	v_mfma_f32_16x16x32_bf16 v[116:119], v[140:143], v[164:167], v[116:119]
	v_mfma_f32_16x16x32_bf16 v[100:103], v[132:135], v[172:175], v[100:103]
	v_mfma_f32_16x16x32_bf16 v[96:99], v[140:143], v[172:175], v[96:99]
	v_mfma_f32_16x16x32_bf16 v[84:87], v[132:135], v[180:183], v[84:87]
	v_mfma_f32_16x16x32_bf16 v[80:83], v[140:143], v[180:183], v[80:83]
	v_mfma_f32_16x16x32_bf16 v[52:55], v[132:135], v[188:191], v[52:55]
	v_mfma_f32_16x16x32_bf16 v[48:51], v[140:143], v[188:191], v[48:51]
	s_setprio 0
	s_setprio 1
	v_mfma_f32_16x16x32_bf16 v[124:127], v[144:147], v[160:163], v[124:127]
	v_mfma_f32_16x16x32_bf16 v[120:123], v[152:155], v[160:163], v[120:123]
	v_mfma_f32_16x16x32_bf16 v[108:111], v[144:147], v[168:171], v[108:111]
	v_mfma_f32_16x16x32_bf16 v[104:107], v[152:155], v[168:171], v[104:107]
	v_mfma_f32_16x16x32_bf16 v[92:95], v[144:147], v[176:179], v[92:95]
	v_mfma_f32_16x16x32_bf16 v[88:91], v[152:155], v[176:179], v[88:91]
	v_mfma_f32_16x16x32_bf16 v[68:71], v[144:147], v[184:187], v[68:71]
	v_mfma_f32_16x16x32_bf16 v[64:67], v[152:155], v[184:187], v[64:67]
	v_mfma_f32_16x16x32_bf16 v[124:127], v[148:151], v[164:167], v[124:127]
	v_mfma_f32_16x16x32_bf16 v[120:123], v[156:159], v[164:167], v[120:123]
	v_mfma_f32_16x16x32_bf16 v[108:111], v[148:151], v[172:175], v[108:111]
	v_mfma_f32_16x16x32_bf16 v[104:107], v[156:159], v[172:175], v[104:107]
	v_mfma_f32_16x16x32_bf16 v[92:95], v[148:151], v[180:183], v[92:95]
	v_mfma_f32_16x16x32_bf16 v[88:91], v[156:159], v[180:183], v[88:91]
	v_mfma_f32_16x16x32_bf16 v[68:71], v[148:151], v[188:191], v[68:71]
	v_mfma_f32_16x16x32_bf16 v[64:67], v[156:159], v[188:191], v[64:67]
	s_barrier
	s_setprio 0
	s_add_i32 s48, s76, s97
	v_lshl_add_u64 v[192:193], v[192:193], 0, s[16:17]
	s_mov_b32 m0, s48
	ds_read_b128 v[160:163], v246 offset:49152
	ds_read_b128 v[164:167], v246 offset:50176
	ds_read_b128 v[168:171], v246 offset:51200
	ds_read_b128 v[172:175], v246 offset:52224
	ds_read_b128 v[176:179], v246 offset:53248
	ds_read_b128 v[180:183], v246 offset:54272
	ds_read_b128 v[184:187], v246 offset:55296
	ds_read_b128 v[188:191], v246 offset:56320
	global_load_lds_dwordx4 v[192:193], off
	s_add_i32 m0, s48, 0x2000
	s_add_u32 s46, s46, 0x100080
	v_lshl_add_u64 v[192:193], v[194:195], 0, s[16:17]
	s_addc_u32 s47, s47, 0
	s_add_i32 s48, s77, s97
	global_load_lds_dwordx4 v[192:193], off
	v_lshl_add_u64 v[192:193], s[46:47], 0, v[210:211]
	s_mov_b32 m0, s48
	s_nop 0
	global_load_lds_dwordx4 v[192:193], off
	v_lshl_add_u64 v[192:193], s[46:47], 0, v[214:215]
	s_add_i32 m0, s48, 0x2000
	s_nop 0
	global_load_lds_dwordx4 v[192:193], off
	v_lshl_add_u64 v[192:193], v[196:197], 0, s[16:17]
	s_mov_b32 m0, s54
	s_nop 0
	global_load_lds_dwordx4 v[192:193], off
	v_lshl_add_u64 v[192:193], v[198:199], 0, s[16:17]
	s_mov_b32 m0, s55
	s_nop 0
	global_load_lds_dwordx4 v[192:193], off
	s_waitcnt vmcnt(8)
	s_waitcnt lgkmcnt(0)
	s_setprio 1
	s_barrier
	v_mfma_f32_16x16x32_bf16 v[60:63], v[128:131], v[160:163], v[60:63]
	v_mfma_f32_16x16x32_bf16 v[56:59], v[136:139], v[160:163], v[56:59]
	v_mfma_f32_16x16x32_bf16 v[36:39], v[128:131], v[168:171], v[36:39]
	v_mfma_f32_16x16x32_bf16 v[32:35], v[136:139], v[168:171], v[32:35]
	v_mfma_f32_16x16x32_bf16 v[20:23], v[128:131], v[176:179], v[20:23]
	v_mfma_f32_16x16x32_bf16 v[16:19], v[136:139], v[176:179], v[16:19]
	v_mfma_f32_16x16x32_bf16 v[4:7], v[128:131], v[184:187], v[4:7]
	v_mfma_f32_16x16x32_bf16 v[0:3], v[136:139], v[184:187], v[0:3]
	v_mfma_f32_16x16x32_bf16 v[60:63], v[132:135], v[164:167], v[60:63]
	v_mfma_f32_16x16x32_bf16 v[56:59], v[140:143], v[164:167], v[56:59]
	v_mfma_f32_16x16x32_bf16 v[36:39], v[132:135], v[172:175], v[36:39]
	v_mfma_f32_16x16x32_bf16 v[32:35], v[140:143], v[172:175], v[32:35]
	v_mfma_f32_16x16x32_bf16 v[20:23], v[132:135], v[180:183], v[20:23]
	v_mfma_f32_16x16x32_bf16 v[16:19], v[140:143], v[180:183], v[16:19]
	v_mfma_f32_16x16x32_bf16 v[4:7], v[132:135], v[188:191], v[4:7]
	v_mfma_f32_16x16x32_bf16 v[0:3], v[140:143], v[188:191], v[0:3]
	s_setprio 0
	s_setprio 1
	v_mfma_f32_16x16x32_bf16 v[76:79], v[144:147], v[160:163], v[76:79]
	v_mfma_f32_16x16x32_bf16 v[72:75], v[152:155], v[160:163], v[72:75]
	v_mfma_f32_16x16x32_bf16 v[44:47], v[144:147], v[168:171], v[44:47]
	v_mfma_f32_16x16x32_bf16 v[40:43], v[152:155], v[168:171], v[40:43]
	v_mfma_f32_16x16x32_bf16 v[28:31], v[144:147], v[176:179], v[28:31]
	v_mfma_f32_16x16x32_bf16 v[24:27], v[152:155], v[176:179], v[24:27]
	v_mfma_f32_16x16x32_bf16 v[12:15], v[144:147], v[184:187], v[12:15]
	v_mfma_f32_16x16x32_bf16 v[8:11], v[152:155], v[184:187], v[8:11]
	v_mfma_f32_16x16x32_bf16 v[76:79], v[148:151], v[164:167], v[76:79]
	v_mfma_f32_16x16x32_bf16 v[72:75], v[156:159], v[164:167], v[72:75]
	v_mfma_f32_16x16x32_bf16 v[44:47], v[148:151], v[172:175], v[44:47]
	v_mfma_f32_16x16x32_bf16 v[40:43], v[156:159], v[172:175], v[40:43]
	v_mfma_f32_16x16x32_bf16 v[28:31], v[148:151], v[180:183], v[28:31]
	v_mfma_f32_16x16x32_bf16 v[24:27], v[156:159], v[180:183], v[24:27]
	v_mfma_f32_16x16x32_bf16 v[12:15], v[148:151], v[188:191], v[12:15]
	v_mfma_f32_16x16x32_bf16 v[8:11], v[156:159], v[188:191], v[8:11]
	s_barrier
	s_setprio 0
	s_add_u32 s69, s69, 0x100
	s_addc_u32 s70, s70, 0
	s_add_u32 s44, s44, 0x100
	s_addc_u32 s45, s45, 0
	s_cmp_ge_u32 s71, s67
	s_mov_b32 s46, s71
	s_cbranch_scc0 .LBB0_2020
	v_readlane_b32 s44, v254, 27
	v_readlane_b32 s45, v254, 28
	s_and_b64 vcc, exec, s[44:45]
	s_cbranch_vccz .LBB0_2028
	s_barrier
	s_cmp_lt_i32 s14, 0
	s_mov_b64 s[44:45], -1
	s_cbranch_scc1 .LBB0_2029

.LBB0_2289:
	ds_read_b128 v[148:151], v159
	ds_read_b128 v[164:167], v159 offset:1024
	ds_read_b128 v[168:171], v159 offset:2048
	ds_read_b128 v[172:175], v159 offset:3072
	ds_read_b128 v[176:179], v160
	ds_read_b128 v[180:183], v160 offset:1024
	ds_read_b128 v[184:187], v160 offset:2048
	ds_read_b128 v[188:191], v160 offset:3072
	s_add_i32 s87, s46, 2
	s_add_u32 s47, s44, 0xfff00080
	s_addc_u32 s48, s45, -1
	s_cmp_eq_u32 s43, s46
	s_cselect_b32 s46, s25, s85
	s_cselect_b32 s49, s37, s48
	s_cselect_b32 s48, s36, s47
	s_cselect_b32 s47, s5, s86
	v_lshl_add_u64 v[152:153], s[44:45], 0, v[142:143]
	s_add_i32 m0, s94, 0xc000
	ds_read_b128 v[192:195], v161
	ds_read_b128 v[196:199], v161 offset:1024
	ds_read_b128 v[200:203], v161 offset:2048
	ds_read_b128 v[204:207], v161 offset:3072
	ds_read_b128 v[208:211], v161 offset:4096
	ds_read_b128 v[212:215], v161 offset:5120
	ds_read_b128 v[216:219], v161 offset:6144
	ds_read_b128 v[220:223], v161 offset:7168
	global_load_lds_dwordx4 v[152:153], off
	v_lshl_add_u64 v[152:153], s[44:45], 0, v[144:145]
	s_add_i32 m0, s94, 0xe000
	s_nop 0
	global_load_lds_dwordx4 v[152:153], off
	s_waitcnt vmcnt(8)
	s_waitcnt lgkmcnt(0)
	s_setprio 1
	s_barrier
	v_mfma_f32_16x16x32_bf16 v[112:115], v[148:151], v[192:195], v[112:115]
	v_mfma_f32_16x16x32_bf16 v[116:119], v[168:171], v[192:195], v[116:119]
	v_mfma_f32_16x16x32_bf16 v[100:103], v[148:151], v[200:203], v[100:103]
	v_mfma_f32_16x16x32_bf16 v[96:99], v[168:171], v[200:203], v[96:99]
	v_mfma_f32_16x16x32_bf16 v[84:87], v[148:151], v[208:211], v[84:87]
	v_mfma_f32_16x16x32_bf16 v[80:83], v[168:171], v[208:211], v[80:83]
	v_mfma_f32_16x16x32_bf16 v[52:55], v[148:151], v[216:219], v[52:55]
	v_mfma_f32_16x16x32_bf16 v[48:51], v[168:171], v[216:219], v[48:51]
	v_mfma_f32_16x16x32_bf16 v[112:115], v[164:167], v[196:199], v[112:115]
	v_mfma_f32_16x16x32_bf16 v[116:119], v[172:175], v[196:199], v[116:119]
	v_mfma_f32_16x16x32_bf16 v[100:103], v[164:167], v[204:207], v[100:103]
	v_mfma_f32_16x16x32_bf16 v[96:99], v[172:175], v[204:207], v[96:99]
	v_mfma_f32_16x16x32_bf16 v[84:87], v[164:167], v[212:215], v[84:87]
	v_mfma_f32_16x16x32_bf16 v[80:83], v[172:175], v[212:215], v[80:83]
	v_mfma_f32_16x16x32_bf16 v[52:55], v[164:167], v[220:223], v[52:55]
	v_mfma_f32_16x16x32_bf16 v[48:51], v[172:175], v[220:223], v[48:51]
	s_setprio 0
	s_setprio 1
	v_mfma_f32_16x16x32_bf16 v[124:127], v[176:179], v[192:195], v[124:127]
	v_mfma_f32_16x16x32_bf16 v[120:123], v[184:187], v[192:195], v[120:123]
	v_mfma_f32_16x16x32_bf16 v[108:111], v[176:179], v[200:203], v[108:111]
	v_mfma_f32_16x16x32_bf16 v[104:107], v[184:187], v[200:203], v[104:107]
	v_mfma_f32_16x16x32_bf16 v[92:95], v[176:179], v[208:211], v[92:95]
	v_mfma_f32_16x16x32_bf16 v[88:91], v[184:187], v[208:211], v[88:91]
	v_mfma_f32_16x16x32_bf16 v[68:71], v[176:179], v[216:219], v[68:71]
	v_mfma_f32_16x16x32_bf16 v[64:67], v[184:187], v[216:219], v[64:67]
	v_mfma_f32_16x16x32_bf16 v[124:127], v[180:183], v[196:199], v[124:127]
	v_mfma_f32_16x16x32_bf16 v[120:123], v[188:191], v[196:199], v[120:123]
	v_mfma_f32_16x16x32_bf16 v[108:111], v[180:183], v[204:207], v[108:111]
	v_mfma_f32_16x16x32_bf16 v[104:107], v[188:191], v[204:207], v[104:107]
	v_mfma_f32_16x16x32_bf16 v[92:95], v[180:183], v[212:215], v[92:95]
	v_mfma_f32_16x16x32_bf16 v[88:91], v[188:191], v[212:215], v[88:91]
	v_mfma_f32_16x16x32_bf16 v[68:71], v[180:183], v[220:223], v[68:71]
	v_mfma_f32_16x16x32_bf16 v[64:67], v[188:191], v[220:223], v[64:67]
	s_barrier
	s_setprio 0
	s_add_i32 s88, s77, s97
	v_lshl_add_u64 v[152:153], s[46:47], 0, v[132:133]
	s_mov_b32 m0, s88
	ds_read_b128 v[192:195], v161 offset:16384
	ds_read_b128 v[196:199], v161 offset:17408
	ds_read_b128 v[200:203], v161 offset:18432
	ds_read_b128 v[204:207], v161 offset:19456
	ds_read_b128 v[208:211], v161 offset:20480
	ds_read_b128 v[212:215], v161 offset:21504
	ds_read_b128 v[216:219], v161 offset:22528
	ds_read_b128 v[220:223], v161 offset:23552
	global_load_lds_dwordx4 v[152:153], off
	s_add_i32 m0, s88, 0x2000
	s_add_u32 s88, s46, 0x100000
	v_lshl_add_u64 v[224:225], s[46:47], 0, v[136:137]
	s_addc_u32 s89, s47, 0
	s_add_i32 s90, s78, s97
	global_load_lds_dwordx4 v[224:225], off
	v_lshl_add_u64 v[226:227], s[88:89], 0, v[132:133]
	s_mov_b32 m0, s90
	v_lshl_add_u64 v[228:229], s[48:49], 0, v[134:135]
	global_load_lds_dwordx4 v[226:227], off
	v_lshl_add_u64 v[226:227], s[88:89], 0, v[136:137]
	s_add_i32 m0, s90, 0x2000
	s_nop 0
	global_load_lds_dwordx4 v[226:227], off
	v_lshl_add_u64 v[226:227], s[48:49], 0, v[130:131]
	s_mov_b32 m0, s94
	s_nop 0
	global_load_lds_dwordx4 v[226:227], off
	s_mov_b32 m0, s52
	s_nop 0
	global_load_lds_dwordx4 v[228:229], off
	s_waitcnt vmcnt(8)
	s_waitcnt lgkmcnt(0)
	s_setprio 1
	s_barrier
	v_mfma_f32_16x16x32_bf16 v[60:63], v[148:151], v[192:195], v[60:63]
	v_mfma_f32_16x16x32_bf16 v[56:59], v[168:171], v[192:195], v[56:59]
	v_mfma_f32_16x16x32_bf16 v[36:39], v[148:151], v[200:203], v[36:39]
	v_mfma_f32_16x16x32_bf16 v[32:35], v[168:171], v[200:203], v[32:35]
	v_mfma_f32_16x16x32_bf16 v[20:23], v[148:151], v[208:211], v[20:23]
	v_mfma_f32_16x16x32_bf16 v[16:19], v[168:171], v[208:211], v[16:19]
	v_mfma_f32_16x16x32_bf16 v[4:7], v[148:151], v[216:219], v[4:7]
	v_mfma_f32_16x16x32_bf16 v[0:3], v[168:171], v[216:219], v[0:3]
	v_mfma_f32_16x16x32_bf16 v[60:63], v[164:167], v[196:199], v[60:63]
	v_mfma_f32_16x16x32_bf16 v[56:59], v[172:175], v[196:199], v[56:59]
	v_mfma_f32_16x16x32_bf16 v[36:39], v[164:167], v[204:207], v[36:39]
	v_mfma_f32_16x16x32_bf16 v[32:35], v[172:175], v[204:207], v[32:35]
	v_mfma_f32_16x16x32_bf16 v[20:23], v[164:167], v[212:215], v[20:23]
	v_mfma_f32_16x16x32_bf16 v[16:19], v[172:175], v[212:215], v[16:19]
	v_mfma_f32_16x16x32_bf16 v[4:7], v[164:167], v[220:223], v[4:7]
	v_mfma_f32_16x16x32_bf16 v[0:3], v[172:175], v[220:223], v[0:3]
	s_setprio 0
	s_setprio 1
	v_mfma_f32_16x16x32_bf16 v[76:79], v[176:179], v[192:195], v[76:79]
	v_mfma_f32_16x16x32_bf16 v[72:75], v[184:187], v[192:195], v[72:75]
	v_mfma_f32_16x16x32_bf16 v[44:47], v[176:179], v[200:203], v[44:47]
	v_mfma_f32_16x16x32_bf16 v[40:43], v[184:187], v[200:203], v[40:43]
	v_mfma_f32_16x16x32_bf16 v[28:31], v[176:179], v[208:211], v[28:31]
	v_mfma_f32_16x16x32_bf16 v[24:27], v[184:187], v[208:211], v[24:27]
	v_mfma_f32_16x16x32_bf16 v[12:15], v[176:179], v[216:219], v[12:15]
	v_mfma_f32_16x16x32_bf16 v[8:11], v[184:187], v[216:219], v[8:11]
	v_mfma_f32_16x16x32_bf16 v[76:79], v[180:183], v[196:199], v[76:79]
	v_mfma_f32_16x16x32_bf16 v[72:75], v[188:191], v[196:199], v[72:75]
	v_mfma_f32_16x16x32_bf16 v[44:47], v[180:183], v[204:207], v[44:47]
	v_mfma_f32_16x16x32_bf16 v[40:43], v[188:191], v[204:207], v[40:43]
	v_mfma_f32_16x16x32_bf16 v[28:31], v[180:183], v[212:215], v[28:31]
	v_mfma_f32_16x16x32_bf16 v[24:27], v[188:191], v[212:215], v[24:27]
	v_mfma_f32_16x16x32_bf16 v[12:15], v[180:183], v[220:223], v[12:15]
	v_mfma_f32_16x16x32_bf16 v[8:11], v[188:191], v[220:223], v[8:11]
	s_barrier
	s_setprio 0
	s_add_i32 s88, 0, 0x18000
	v_add_u32_e32 v163, s88, v157
	s_add_i32 s89, 0, 0x1c000
	ds_read_b128 v[148:151], v163
	ds_read_b128 v[164:167], v163 offset:1024
	ds_read_b128 v[168:171], v163 offset:2048
	ds_read_b128 v[172:175], v163 offset:3072
	v_add_u32_e32 v163, s89, v157
	ds_read_b128 v[176:179], v163
	ds_read_b128 v[180:183], v163 offset:1024
	ds_read_b128 v[184:187], v163 offset:2048
	ds_read_b128 v[188:191], v163 offset:3072
	s_add_u32 s48, s48, 0x100000
	s_addc_u32 s49, s49, 0
	s_mov_b32 m0, s53
	v_lshl_add_u64 v[230:231], s[48:49], 0, v[130:131]
	ds_read_b128 v[192:195], v161 offset:32768
	ds_read_b128 v[196:199], v161 offset:33792
	ds_read_b128 v[200:203], v161 offset:34816
	ds_read_b128 v[204:207], v161 offset:35840
	ds_read_b128 v[208:211], v161 offset:36864
	ds_read_b128 v[212:215], v161 offset:37888
	ds_read_b128 v[216:219], v161 offset:38912
	ds_read_b128 v[220:223], v161 offset:39936
	global_load_lds_dwordx4 v[230:231], off
	v_lshl_add_u64 v[230:231], s[48:49], 0, v[134:135]
	s_mov_b32 m0, s54
	s_nop 0
	global_load_lds_dwordx4 v[230:231], off
	s_waitcnt vmcnt(8)
	s_waitcnt lgkmcnt(0)
	s_setprio 1
	s_barrier
	v_mfma_f32_16x16x32_bf16 v[112:115], v[148:151], v[192:195], v[112:115]
	v_mfma_f32_16x16x32_bf16 v[116:119], v[168:171], v[192:195], v[116:119]
	v_mfma_f32_16x16x32_bf16 v[100:103], v[148:151], v[200:203], v[100:103]
	v_mfma_f32_16x16x32_bf16 v[96:99], v[168:171], v[200:203], v[96:99]
	v_mfma_f32_16x16x32_bf16 v[84:87], v[148:151], v[208:211], v[84:87]
	v_mfma_f32_16x16x32_bf16 v[80:83], v[168:171], v[208:211], v[80:83]
	v_mfma_f32_16x16x32_bf16 v[52:55], v[148:151], v[216:219], v[52:55]
	v_mfma_f32_16x16x32_bf16 v[48:51], v[168:171], v[216:219], v[48:51]
	v_mfma_f32_16x16x32_bf16 v[112:115], v[164:167], v[196:199], v[112:115]
	v_mfma_f32_16x16x32_bf16 v[116:119], v[172:175], v[196:199], v[116:119]
	v_mfma_f32_16x16x32_bf16 v[100:103], v[164:167], v[204:207], v[100:103]
	v_mfma_f32_16x16x32_bf16 v[96:99], v[172:175], v[204:207], v[96:99]
	v_mfma_f32_16x16x32_bf16 v[84:87], v[164:167], v[212:215], v[84:87]
	v_mfma_f32_16x16x32_bf16 v[80:83], v[172:175], v[212:215], v[80:83]
	v_mfma_f32_16x16x32_bf16 v[52:55], v[164:167], v[220:223], v[52:55]
	v_mfma_f32_16x16x32_bf16 v[48:51], v[172:175], v[220:223], v[48:51]
	s_setprio 0
	s_setprio 1
	v_mfma_f32_16x16x32_bf16 v[124:127], v[176:179], v[192:195], v[124:127]
	v_mfma_f32_16x16x32_bf16 v[120:123], v[184:187], v[192:195], v[120:123]
	v_mfma_f32_16x16x32_bf16 v[108:111], v[176:179], v[200:203], v[108:111]
	v_mfma_f32_16x16x32_bf16 v[104:107], v[184:187], v[200:203], v[104:107]
	v_mfma_f32_16x16x32_bf16 v[92:95], v[176:179], v[208:211], v[92:95]
	v_mfma_f32_16x16x32_bf16 v[88:91], v[184:187], v[208:211], v[88:91]
	v_mfma_f32_16x16x32_bf16 v[68:71], v[176:179], v[216:219], v[68:71]
	v_mfma_f32_16x16x32_bf16 v[64:67], v[184:187], v[216:219], v[64:67]
	v_mfma_f32_16x16x32_bf16 v[124:127], v[180:183], v[196:199], v[124:127]
	v_mfma_f32_16x16x32_bf16 v[120:123], v[188:191], v[196:199], v[120:123]
	v_mfma_f32_16x16x32_bf16 v[108:111], v[180:183], v[204:207], v[108:111]
	v_mfma_f32_16x16x32_bf16 v[104:107], v[188:191], v[204:207], v[104:107]
	v_mfma_f32_16x16x32_bf16 v[92:95], v[180:183], v[212:215], v[92:95]
	v_mfma_f32_16x16x32_bf16 v[88:91], v[188:191], v[212:215], v[88:91]
	v_mfma_f32_16x16x32_bf16 v[68:71], v[180:183], v[220:223], v[68:71]
	v_mfma_f32_16x16x32_bf16 v[64:67], v[188:191], v[220:223], v[64:67]
	s_barrier
	s_setprio 0
	s_add_i32 s48, s88, s97
	v_lshl_add_u64 v[152:153], v[152:153], 0, s[18:19]
	s_mov_b32 m0, s48
	ds_read_b128 v[192:195], v161 offset:49152
	ds_read_b128 v[196:199], v161 offset:50176
	ds_read_b128 v[200:203], v161 offset:51200
	ds_read_b128 v[204:207], v161 offset:52224
	ds_read_b128 v[208:211], v161 offset:53248
	ds_read_b128 v[212:215], v161 offset:54272
	ds_read_b128 v[216:219], v161 offset:55296
	ds_read_b128 v[220:223], v161 offset:56320
	global_load_lds_dwordx4 v[152:153], off
	s_add_i32 m0, s48, 0x2000
	s_add_u32 s46, s46, 0x100080
	v_lshl_add_u64 v[152:153], v[224:225], 0, s[18:19]
	s_addc_u32 s47, s47, 0
	s_add_i32 s48, s89, s97
	global_load_lds_dwordx4 v[152:153], off
	v_lshl_add_u64 v[152:153], s[46:47], 0, v[132:133]
	s_mov_b32 m0, s48
	s_nop 0
	global_load_lds_dwordx4 v[152:153], off
	v_lshl_add_u64 v[152:153], s[46:47], 0, v[136:137]
	s_add_i32 m0, s48, 0x2000
	s_nop 0
	global_load_lds_dwordx4 v[152:153], off
	v_lshl_add_u64 v[152:153], v[226:227], 0, s[18:19]
	s_mov_b32 m0, s68
	s_nop 0
	global_load_lds_dwordx4 v[152:153], off
	v_lshl_add_u64 v[152:153], v[228:229], 0, s[18:19]
	s_mov_b32 m0, s69
	s_nop 0
	global_load_lds_dwordx4 v[152:153], off
	s_waitcnt vmcnt(8)
	s_waitcnt lgkmcnt(0)
	s_setprio 1
	s_barrier
	v_mfma_f32_16x16x32_bf16 v[60:63], v[148:151], v[192:195], v[60:63]
	v_mfma_f32_16x16x32_bf16 v[56:59], v[168:171], v[192:195], v[56:59]
	v_mfma_f32_16x16x32_bf16 v[36:39], v[148:151], v[200:203], v[36:39]
	v_mfma_f32_16x16x32_bf16 v[32:35], v[168:171], v[200:203], v[32:35]
	v_mfma_f32_16x16x32_bf16 v[20:23], v[148:151], v[208:211], v[20:23]
	v_mfma_f32_16x16x32_bf16 v[16:19], v[168:171], v[208:211], v[16:19]
	v_mfma_f32_16x16x32_bf16 v[4:7], v[148:151], v[216:219], v[4:7]
	v_mfma_f32_16x16x32_bf16 v[0:3], v[168:171], v[216:219], v[0:3]
	v_mfma_f32_16x16x32_bf16 v[60:63], v[164:167], v[196:199], v[60:63]
	v_mfma_f32_16x16x32_bf16 v[56:59], v[172:175], v[196:199], v[56:59]
	v_mfma_f32_16x16x32_bf16 v[36:39], v[164:167], v[204:207], v[36:39]
	v_mfma_f32_16x16x32_bf16 v[32:35], v[172:175], v[204:207], v[32:35]
	v_mfma_f32_16x16x32_bf16 v[20:23], v[164:167], v[212:215], v[20:23]
	v_mfma_f32_16x16x32_bf16 v[16:19], v[172:175], v[212:215], v[16:19]
	v_mfma_f32_16x16x32_bf16 v[4:7], v[164:167], v[220:223], v[4:7]
	v_mfma_f32_16x16x32_bf16 v[0:3], v[172:175], v[220:223], v[0:3]
	s_setprio 0
	s_setprio 1
	v_mfma_f32_16x16x32_bf16 v[76:79], v[176:179], v[192:195], v[76:79]
	v_mfma_f32_16x16x32_bf16 v[72:75], v[184:187], v[192:195], v[72:75]
	v_mfma_f32_16x16x32_bf16 v[44:47], v[176:179], v[200:203], v[44:47]
	v_mfma_f32_16x16x32_bf16 v[40:43], v[184:187], v[200:203], v[40:43]
	v_mfma_f32_16x16x32_bf16 v[28:31], v[176:179], v[208:211], v[28:31]
	v_mfma_f32_16x16x32_bf16 v[24:27], v[184:187], v[208:211], v[24:27]
	v_mfma_f32_16x16x32_bf16 v[12:15], v[176:179], v[216:219], v[12:15]
	v_mfma_f32_16x16x32_bf16 v[8:11], v[184:187], v[216:219], v[8:11]
	v_mfma_f32_16x16x32_bf16 v[76:79], v[180:183], v[196:199], v[76:79]
	v_mfma_f32_16x16x32_bf16 v[72:75], v[188:191], v[196:199], v[72:75]
	v_mfma_f32_16x16x32_bf16 v[44:47], v[180:183], v[204:207], v[44:47]
	v_mfma_f32_16x16x32_bf16 v[40:43], v[188:191], v[204:207], v[40:43]
	v_mfma_f32_16x16x32_bf16 v[28:31], v[180:183], v[212:215], v[28:31]
	v_mfma_f32_16x16x32_bf16 v[24:27], v[188:191], v[212:215], v[24:27]
	v_mfma_f32_16x16x32_bf16 v[12:15], v[180:183], v[220:223], v[12:15]
	v_mfma_f32_16x16x32_bf16 v[8:11], v[188:191], v[220:223], v[8:11]
	s_barrier
	s_setprio 0
	s_add_u32 s85, s85, 0x100
	s_addc_u32 s86, s86, 0
	s_add_u32 s44, s44, 0x100
	s_addc_u32 s45, s45, 0
	s_cmp_ge_u32 s87, s84
	s_mov_b32 s46, s87
	s_cbranch_scc0 .LBB0_2289
	v_readlane_b32 s44, v254, 27
	v_readlane_b32 s45, v254, 28
	s_and_b64 vcc, exec, s[44:45]
	s_cbranch_vccz .LBB0_2297
	s_barrier
	s_cmp_lt_i32 s16, 0
	s_mov_b64 s[44:45], -1
	s_cbranch_scc1 .LBB0_2298

.LBB0_2453:
	ds_read_b128 v[128:131], v228
	ds_read_b128 v[132:135], v228 offset:1024
	ds_read_b128 v[136:139], v228 offset:2048
	ds_read_b128 v[140:143], v228 offset:3072
	ds_read_b128 v[144:147], v229
	ds_read_b128 v[148:151], v229 offset:1024
	ds_read_b128 v[152:155], v229 offset:2048
	ds_read_b128 v[156:159], v229 offset:3072
	s_add_i32 s79, s46, 2
	s_add_u32 s47, s44, 0xffc00080
	s_addc_u32 s48, s45, -1
	s_cmp_eq_u32 s75, s46
	s_cselect_b32 s46, s43, s77
	s_cselect_b32 s49, s35, s48
	s_cselect_b32 s48, s41, s47
	s_cselect_b32 s47, s31, s78
	v_lshl_add_u64 v[208:209], s[44:45], 0, v[202:203]
	s_add_i32 m0, s94, 0xc000
	ds_read_b128 v[160:163], v230
	ds_read_b128 v[164:167], v230 offset:1024
	ds_read_b128 v[168:171], v230 offset:2048
	ds_read_b128 v[172:175], v230 offset:3072
	ds_read_b128 v[176:179], v230 offset:4096
	ds_read_b128 v[180:183], v230 offset:5120
	ds_read_b128 v[184:187], v230 offset:6144
	ds_read_b128 v[188:191], v230 offset:7168
	global_load_lds_dwordx4 v[208:209], off
	v_lshl_add_u64 v[208:209], s[44:45], 0, v[204:205]
	s_add_i32 m0, s94, 0xe000
	s_nop 0
	global_load_lds_dwordx4 v[208:209], off
	s_waitcnt vmcnt(8)
	s_waitcnt lgkmcnt(0)
	s_setprio 1
	s_barrier
	v_mfma_f32_16x16x32_bf16 v[112:115], v[128:131], v[160:163], v[112:115]
	v_mfma_f32_16x16x32_bf16 v[116:119], v[136:139], v[160:163], v[116:119]
	v_mfma_f32_16x16x32_bf16 v[100:103], v[128:131], v[168:171], v[100:103]
	v_mfma_f32_16x16x32_bf16 v[96:99], v[136:139], v[168:171], v[96:99]
	v_mfma_f32_16x16x32_bf16 v[84:87], v[128:131], v[176:179], v[84:87]
	v_mfma_f32_16x16x32_bf16 v[80:83], v[136:139], v[176:179], v[80:83]
	v_mfma_f32_16x16x32_bf16 v[52:55], v[128:131], v[184:187], v[52:55]
	v_mfma_f32_16x16x32_bf16 v[48:51], v[136:139], v[184:187], v[48:51]
	v_mfma_f32_16x16x32_bf16 v[112:115], v[132:135], v[164:167], v[112:115]
	v_mfma_f32_16x16x32_bf16 v[116:119], v[140:143], v[164:167], v[116:119]
	v_mfma_f32_16x16x32_bf16 v[100:103], v[132:135], v[172:175], v[100:103]
	v_mfma_f32_16x16x32_bf16 v[96:99], v[140:143], v[172:175], v[96:99]
	v_mfma_f32_16x16x32_bf16 v[84:87], v[132:135], v[180:183], v[84:87]
	v_mfma_f32_16x16x32_bf16 v[80:83], v[140:143], v[180:183], v[80:83]
	v_mfma_f32_16x16x32_bf16 v[52:55], v[132:135], v[188:191], v[52:55]
	v_mfma_f32_16x16x32_bf16 v[48:51], v[140:143], v[188:191], v[48:51]
	s_setprio 0
	s_setprio 1
	v_mfma_f32_16x16x32_bf16 v[124:127], v[144:147], v[160:163], v[124:127]
	v_mfma_f32_16x16x32_bf16 v[120:123], v[152:155], v[160:163], v[120:123]
	v_mfma_f32_16x16x32_bf16 v[108:111], v[144:147], v[168:171], v[108:111]
	v_mfma_f32_16x16x32_bf16 v[104:107], v[152:155], v[168:171], v[104:107]
	v_mfma_f32_16x16x32_bf16 v[92:95], v[144:147], v[176:179], v[92:95]
	v_mfma_f32_16x16x32_bf16 v[88:91], v[152:155], v[176:179], v[88:91]
	v_mfma_f32_16x16x32_bf16 v[68:71], v[144:147], v[184:187], v[68:71]
	v_mfma_f32_16x16x32_bf16 v[64:67], v[152:155], v[184:187], v[64:67]
	v_mfma_f32_16x16x32_bf16 v[124:127], v[148:151], v[164:167], v[124:127]
	v_mfma_f32_16x16x32_bf16 v[120:123], v[156:159], v[164:167], v[120:123]
	v_mfma_f32_16x16x32_bf16 v[108:111], v[148:151], v[172:175], v[108:111]
	v_mfma_f32_16x16x32_bf16 v[104:107], v[156:159], v[172:175], v[104:107]
	v_mfma_f32_16x16x32_bf16 v[92:95], v[148:151], v[180:183], v[92:95]
	v_mfma_f32_16x16x32_bf16 v[88:91], v[156:159], v[180:183], v[88:91]
	v_mfma_f32_16x16x32_bf16 v[68:71], v[148:151], v[188:191], v[68:71]
	v_mfma_f32_16x16x32_bf16 v[64:67], v[156:159], v[188:191], v[64:67]
	s_barrier
	s_setprio 0
	s_add_i32 s80, s68, s97
	v_lshl_add_u64 v[208:209], s[46:47], 0, v[194:195]
	s_mov_b32 m0, s80
	ds_read_b128 v[160:163], v230 offset:16384
	ds_read_b128 v[164:167], v230 offset:17408
	ds_read_b128 v[168:171], v230 offset:18432
	ds_read_b128 v[172:175], v230 offset:19456
	ds_read_b128 v[176:179], v230 offset:20480
	ds_read_b128 v[180:183], v230 offset:21504
	ds_read_b128 v[184:187], v230 offset:22528
	ds_read_b128 v[188:191], v230 offset:23552
	global_load_lds_dwordx4 v[208:209], off
	s_add_i32 m0, s80, 0x2000
	s_add_u32 s80, s46, 0x400000
	v_lshl_add_u64 v[210:211], s[46:47], 0, v[198:199]
	s_addc_u32 s81, s47, 0
	s_add_i32 s84, s69, s97
	global_load_lds_dwordx4 v[210:211], off
	v_lshl_add_u64 v[212:213], s[80:81], 0, v[194:195]
	s_mov_b32 m0, s84
	v_lshl_add_u64 v[214:215], s[48:49], 0, v[196:197]
	global_load_lds_dwordx4 v[212:213], off
	v_lshl_add_u64 v[212:213], s[80:81], 0, v[198:199]
	s_add_i32 m0, s84, 0x2000
	s_nop 0
	global_load_lds_dwordx4 v[212:213], off
	v_lshl_add_u64 v[212:213], s[48:49], 0, v[192:193]
	s_mov_b32 m0, s94
	s_nop 0
	global_load_lds_dwordx4 v[212:213], off
	s_mov_b32 m0, s51
	s_nop 0
	global_load_lds_dwordx4 v[214:215], off
	s_waitcnt vmcnt(8)
	s_waitcnt lgkmcnt(0)
	s_setprio 1
	s_barrier
	v_mfma_f32_16x16x32_bf16 v[60:63], v[128:131], v[160:163], v[60:63]
	v_mfma_f32_16x16x32_bf16 v[56:59], v[136:139], v[160:163], v[56:59]
	v_mfma_f32_16x16x32_bf16 v[36:39], v[128:131], v[168:171], v[36:39]
	v_mfma_f32_16x16x32_bf16 v[32:35], v[136:139], v[168:171], v[32:35]
	v_mfma_f32_16x16x32_bf16 v[20:23], v[128:131], v[176:179], v[20:23]
	v_mfma_f32_16x16x32_bf16 v[16:19], v[136:139], v[176:179], v[16:19]
	v_mfma_f32_16x16x32_bf16 v[4:7], v[128:131], v[184:187], v[4:7]
	v_mfma_f32_16x16x32_bf16 v[0:3], v[136:139], v[184:187], v[0:3]
	v_mfma_f32_16x16x32_bf16 v[60:63], v[132:135], v[164:167], v[60:63]
	v_mfma_f32_16x16x32_bf16 v[56:59], v[140:143], v[164:167], v[56:59]
	v_mfma_f32_16x16x32_bf16 v[36:39], v[132:135], v[172:175], v[36:39]
	v_mfma_f32_16x16x32_bf16 v[32:35], v[140:143], v[172:175], v[32:35]
	v_mfma_f32_16x16x32_bf16 v[20:23], v[132:135], v[180:183], v[20:23]
	v_mfma_f32_16x16x32_bf16 v[16:19], v[140:143], v[180:183], v[16:19]
	v_mfma_f32_16x16x32_bf16 v[4:7], v[132:135], v[188:191], v[4:7]
	v_mfma_f32_16x16x32_bf16 v[0:3], v[140:143], v[188:191], v[0:3]
	s_setprio 0
	s_setprio 1
	v_mfma_f32_16x16x32_bf16 v[76:79], v[144:147], v[160:163], v[76:79]
	v_mfma_f32_16x16x32_bf16 v[72:75], v[152:155], v[160:163], v[72:75]
	v_mfma_f32_16x16x32_bf16 v[44:47], v[144:147], v[168:171], v[44:47]
	v_mfma_f32_16x16x32_bf16 v[40:43], v[152:155], v[168:171], v[40:43]
	v_mfma_f32_16x16x32_bf16 v[28:31], v[144:147], v[176:179], v[28:31]
	v_mfma_f32_16x16x32_bf16 v[24:27], v[152:155], v[176:179], v[24:27]
	v_mfma_f32_16x16x32_bf16 v[12:15], v[144:147], v[184:187], v[12:15]
	v_mfma_f32_16x16x32_bf16 v[8:11], v[152:155], v[184:187], v[8:11]
	v_mfma_f32_16x16x32_bf16 v[76:79], v[148:151], v[164:167], v[76:79]
	v_mfma_f32_16x16x32_bf16 v[72:75], v[156:159], v[164:167], v[72:75]
	v_mfma_f32_16x16x32_bf16 v[44:47], v[148:151], v[172:175], v[44:47]
	v_mfma_f32_16x16x32_bf16 v[40:43], v[156:159], v[172:175], v[40:43]
	v_mfma_f32_16x16x32_bf16 v[28:31], v[148:151], v[180:183], v[28:31]
	v_mfma_f32_16x16x32_bf16 v[24:27], v[156:159], v[180:183], v[24:27]
	v_mfma_f32_16x16x32_bf16 v[12:15], v[148:151], v[188:191], v[12:15]
	v_mfma_f32_16x16x32_bf16 v[8:11], v[156:159], v[188:191], v[8:11]
	s_barrier
	s_setprio 0
	s_add_i32 s80, 0, 0x18000
	s_add_i32 s81, 0, 0x1c000
	v_add_u32_e32 v140, s80, v226
	v_add_u32_e32 v156, s81, v226
	ds_read_b128 v[128:131], v140
	ds_read_b128 v[132:135], v140 offset:1024
	ds_read_b128 v[136:139], v140 offset:2048
	ds_read_b128 v[140:143], v140 offset:3072
	ds_read_b128 v[144:147], v156
	ds_read_b128 v[148:151], v156 offset:1024
	ds_read_b128 v[152:155], v156 offset:2048
	ds_read_b128 v[156:159], v156 offset:3072
	s_add_u32 s48, s48, 0x400000
	s_addc_u32 s49, s49, 0
	s_mov_b32 m0, s52
	v_lshl_add_u64 v[216:217], s[48:49], 0, v[192:193]
	ds_read_b128 v[160:163], v230 offset:32768
	ds_read_b128 v[164:167], v230 offset:33792
	ds_read_b128 v[168:171], v230 offset:34816
	ds_read_b128 v[172:175], v230 offset:35840
	ds_read_b128 v[176:179], v230 offset:36864
	ds_read_b128 v[180:183], v230 offset:37888
	ds_read_b128 v[184:187], v230 offset:38912
	ds_read_b128 v[188:191], v230 offset:39936
	global_load_lds_dwordx4 v[216:217], off
	v_lshl_add_u64 v[216:217], s[48:49], 0, v[196:197]
	s_mov_b32 m0, s53
	s_nop 0
	global_load_lds_dwordx4 v[216:217], off
	s_waitcnt vmcnt(8)
	s_waitcnt lgkmcnt(0)
	s_setprio 1
	s_barrier
	v_mfma_f32_16x16x32_bf16 v[112:115], v[128:131], v[160:163], v[112:115]
	v_mfma_f32_16x16x32_bf16 v[116:119], v[136:139], v[160:163], v[116:119]
	v_mfma_f32_16x16x32_bf16 v[100:103], v[128:131], v[168:171], v[100:103]
	v_mfma_f32_16x16x32_bf16 v[96:99], v[136:139], v[168:171], v[96:99]
	v_mfma_f32_16x16x32_bf16 v[84:87], v[128:131], v[176:179], v[84:87]
	v_mfma_f32_16x16x32_bf16 v[80:83], v[136:139], v[176:179], v[80:83]
	v_mfma_f32_16x16x32_bf16 v[52:55], v[128:131], v[184:187], v[52:55]
	v_mfma_f32_16x16x32_bf16 v[48:51], v[136:139], v[184:187], v[48:51]
	v_mfma_f32_16x16x32_bf16 v[112:115], v[132:135], v[164:167], v[112:115]
	v_mfma_f32_16x16x32_bf16 v[116:119], v[140:143], v[164:167], v[116:119]
	v_mfma_f32_16x16x32_bf16 v[100:103], v[132:135], v[172:175], v[100:103]
	v_mfma_f32_16x16x32_bf16 v[96:99], v[140:143], v[172:175], v[96:99]
	v_mfma_f32_16x16x32_bf16 v[84:87], v[132:135], v[180:183], v[84:87]
	v_mfma_f32_16x16x32_bf16 v[80:83], v[140:143], v[180:183], v[80:83]
	v_mfma_f32_16x16x32_bf16 v[52:55], v[132:135], v[188:191], v[52:55]
	v_mfma_f32_16x16x32_bf16 v[48:51], v[140:143], v[188:191], v[48:51]
	s_setprio 0
	s_setprio 1
	v_mfma_f32_16x16x32_bf16 v[124:127], v[144:147], v[160:163], v[124:127]
	v_mfma_f32_16x16x32_bf16 v[120:123], v[152:155], v[160:163], v[120:123]
	v_mfma_f32_16x16x32_bf16 v[108:111], v[144:147], v[168:171], v[108:111]
	v_mfma_f32_16x16x32_bf16 v[104:107], v[152:155], v[168:171], v[104:107]
	v_mfma_f32_16x16x32_bf16 v[92:95], v[144:147], v[176:179], v[92:95]
	v_mfma_f32_16x16x32_bf16 v[88:91], v[152:155], v[176:179], v[88:91]
	v_mfma_f32_16x16x32_bf16 v[68:71], v[144:147], v[184:187], v[68:71]
	v_mfma_f32_16x16x32_bf16 v[64:67], v[152:155], v[184:187], v[64:67]
	v_mfma_f32_16x16x32_bf16 v[124:127], v[148:151], v[164:167], v[124:127]
	v_mfma_f32_16x16x32_bf16 v[120:123], v[156:159], v[164:167], v[120:123]
	v_mfma_f32_16x16x32_bf16 v[108:111], v[148:151], v[172:175], v[108:111]
	v_mfma_f32_16x16x32_bf16 v[104:107], v[156:159], v[172:175], v[104:107]
	v_mfma_f32_16x16x32_bf16 v[92:95], v[148:151], v[180:183], v[92:95]
	v_mfma_f32_16x16x32_bf16 v[88:91], v[156:159], v[180:183], v[88:91]
	v_mfma_f32_16x16x32_bf16 v[68:71], v[148:151], v[188:191], v[68:71]
	v_mfma_f32_16x16x32_bf16 v[64:67], v[156:159], v[188:191], v[64:67]
	s_barrier
	s_setprio 0
	s_add_i32 s48, s80, s97
	v_lshl_add_u64 v[208:209], v[208:209], 0, s[12:13]
	s_mov_b32 m0, s48
	ds_read_b128 v[160:163], v230 offset:49152
	ds_read_b128 v[164:167], v230 offset:50176
	ds_read_b128 v[168:171], v230 offset:51200
	ds_read_b128 v[172:175], v230 offset:52224
	ds_read_b128 v[176:179], v230 offset:53248
	ds_read_b128 v[180:183], v230 offset:54272
	ds_read_b128 v[184:187], v230 offset:55296
	ds_read_b128 v[188:191], v230 offset:56320
	global_load_lds_dwordx4 v[208:209], off
	s_add_i32 m0, s48, 0x2000
	s_add_u32 s46, s46, 0x400080
	v_lshl_add_u64 v[208:209], v[210:211], 0, s[12:13]
	s_addc_u32 s47, s47, 0
	s_add_i32 s48, s81, s97
	global_load_lds_dwordx4 v[208:209], off
	v_lshl_add_u64 v[208:209], s[46:47], 0, v[194:195]
	s_mov_b32 m0, s48
	s_nop 0
	global_load_lds_dwordx4 v[208:209], off
	v_lshl_add_u64 v[208:209], s[46:47], 0, v[198:199]
	s_add_i32 m0, s48, 0x2000
	s_nop 0
	global_load_lds_dwordx4 v[208:209], off
	v_lshl_add_u64 v[208:209], v[212:213], 0, s[12:13]
	s_mov_b32 m0, s54
	s_nop 0
	global_load_lds_dwordx4 v[208:209], off
	v_lshl_add_u64 v[208:209], v[214:215], 0, s[12:13]
	s_mov_b32 m0, s55
	s_nop 0
	global_load_lds_dwordx4 v[208:209], off
	s_waitcnt vmcnt(8)
	s_waitcnt lgkmcnt(0)
	s_setprio 1
	s_barrier
	v_mfma_f32_16x16x32_bf16 v[60:63], v[128:131], v[160:163], v[60:63]
	v_mfma_f32_16x16x32_bf16 v[56:59], v[136:139], v[160:163], v[56:59]
	v_mfma_f32_16x16x32_bf16 v[36:39], v[128:131], v[168:171], v[36:39]
	v_mfma_f32_16x16x32_bf16 v[32:35], v[136:139], v[168:171], v[32:35]
	v_mfma_f32_16x16x32_bf16 v[20:23], v[128:131], v[176:179], v[20:23]
	v_mfma_f32_16x16x32_bf16 v[16:19], v[136:139], v[176:179], v[16:19]
	v_mfma_f32_16x16x32_bf16 v[4:7], v[128:131], v[184:187], v[4:7]
	v_mfma_f32_16x16x32_bf16 v[0:3], v[136:139], v[184:187], v[0:3]
	v_mfma_f32_16x16x32_bf16 v[60:63], v[132:135], v[164:167], v[60:63]
	v_mfma_f32_16x16x32_bf16 v[56:59], v[140:143], v[164:167], v[56:59]
	v_mfma_f32_16x16x32_bf16 v[36:39], v[132:135], v[172:175], v[36:39]
	v_mfma_f32_16x16x32_bf16 v[32:35], v[140:143], v[172:175], v[32:35]
	v_mfma_f32_16x16x32_bf16 v[20:23], v[132:135], v[180:183], v[20:23]
	v_mfma_f32_16x16x32_bf16 v[16:19], v[140:143], v[180:183], v[16:19]
	v_mfma_f32_16x16x32_bf16 v[4:7], v[132:135], v[188:191], v[4:7]
	v_mfma_f32_16x16x32_bf16 v[0:3], v[140:143], v[188:191], v[0:3]
	s_setprio 0
	s_setprio 1
	v_mfma_f32_16x16x32_bf16 v[76:79], v[144:147], v[160:163], v[76:79]
	v_mfma_f32_16x16x32_bf16 v[72:75], v[152:155], v[160:163], v[72:75]
	v_mfma_f32_16x16x32_bf16 v[44:47], v[144:147], v[168:171], v[44:47]
	v_mfma_f32_16x16x32_bf16 v[40:43], v[152:155], v[168:171], v[40:43]
	v_mfma_f32_16x16x32_bf16 v[28:31], v[144:147], v[176:179], v[28:31]
	v_mfma_f32_16x16x32_bf16 v[24:27], v[152:155], v[176:179], v[24:27]
	v_mfma_f32_16x16x32_bf16 v[12:15], v[144:147], v[184:187], v[12:15]
	v_mfma_f32_16x16x32_bf16 v[8:11], v[152:155], v[184:187], v[8:11]
	v_mfma_f32_16x16x32_bf16 v[76:79], v[148:151], v[164:167], v[76:79]
	v_mfma_f32_16x16x32_bf16 v[72:75], v[156:159], v[164:167], v[72:75]
	v_mfma_f32_16x16x32_bf16 v[44:47], v[148:151], v[172:175], v[44:47]
	v_mfma_f32_16x16x32_bf16 v[40:43], v[156:159], v[172:175], v[40:43]
	v_mfma_f32_16x16x32_bf16 v[28:31], v[148:151], v[180:183], v[28:31]
	v_mfma_f32_16x16x32_bf16 v[24:27], v[156:159], v[180:183], v[24:27]
	v_mfma_f32_16x16x32_bf16 v[12:15], v[148:151], v[188:191], v[12:15]
	v_mfma_f32_16x16x32_bf16 v[8:11], v[156:159], v[188:191], v[8:11]
	s_barrier
	s_setprio 0
	s_add_u32 s77, s77, 0x100
	s_addc_u32 s78, s78, 0
	s_add_u32 s44, s44, 0x100
	s_addc_u32 s45, s45, 0
	s_cmp_ge_u32 s79, s76
	s_mov_b32 s46, s79
	s_cbranch_scc0 .LBB0_2453
	v_readlane_b32 s44, v254, 27
	v_readlane_b32 s45, v254, 28
	s_and_b64 vcc, exec, s[44:45]
	s_cbranch_vccz .LBB0_2461
	s_barrier
	s_cmp_lt_i32 s10, 0
	s_mov_b64 s[44:45], -1
	s_cbranch_scc1 .LBB0_2462
